# on top of v2: leading half (wr=0) defers its counted vmcnt wait to the end of the following MFMA segment (one more phase of prefetch lead)
# baseline (speedup 1.0000x reference)
; #define PG8_STAGE(bufoff, gbase, voff) do { _Pragma("unroll") for (int _i = 0; _i < 2; ++_i) \
;         __builtin_amdgcn_global_load_lds((const unsigned*)((const char*)(gbase) + (voff)[_i]), (PG8_LAS unsigned*)(lds + (bufoff) + ldsw + _i * 8192), 16, 0, 0); } while (0)
; #define PG8_LDA(dst, b, h) do { _Pragma("unroll") for (int m = 0; m < 4; ++m) _Pragma("unroll") for (int k = 0; k < 2; ++k) dst[m][k] = *(const PG8_LAS bf16x8*)(lds + PG8_SA(b, h) + aoff + m * 2048 + k * 1024); } while (0)
; #define PG8_LDB(dst, b, h) do { _Pragma("unroll") for (int n = 0; n < 2; ++n) _Pragma("unroll") for (int k = 0; k < 2; ++k) dst[n][k] = *(const PG8_LAS bf16x8*)(lds + PG8_SB(b, h) + boff + n * 2048 + k * 1024); } while (0)
; #define PG8_MMA(ai, bj, At, Bt) do { __builtin_amdgcn_s_setprio(1); _Pragma("unroll") for (int m = 0; m < 4; ++m) _Pragma("unroll") for (int n = 0; n < 2; ++n) _Pragma("unroll") for (int k = 0; k < 2; ++k) \
;         acc[ai][bj][m][n] = __builtin_amdgcn_mfma_f32_16x16x32_bf16(Bt[n][k], At[m][k], acc[ai][bj][m][n], 0, 0, 0); __builtin_amdgcn_s_setprio(0); } while (0)
; #define PG8_WAIT_V(n) asm volatile("s_waitcnt vmcnt(" #n ")" ::: "memory")
; #define PG8_WAIT_L(n) asm volatile("s_waitcnt lgkmcnt(" #n ")" ::: "memory")
; #define PG8_BAR __builtin_amdgcn_s_barrier()
; #define PG8_SCHED __builtin_amdgcn_sched_barrier(0)
; template <class Epi, class Sched, bool ALIGN_EPI = false, bool SP2 = false>
; __device__ __forceinline__ void gemm_phase(PG8_LAS unsigned char* lds, const Gemm g, const Sched& S, const Epi& E, const int wave_id) {
;     ...
;             PG8_LDB(B0, 0, 0); PG8_LDB(B1, 0, 1); PG8_SCHED; PG8_LDA(At, 0, 0); PG8_STAGE(PG8_SA(1, 1), a1 + hstep, voffA);
;             PG8_WAIT_V(8); PG8_WAIT_L(0); PG8_BAR; PG8_MMA(0, 0, At, B0); PG8_MMA(0, 1, At, B1); PG8_BAR; PG8_SCHED;
;             PG8_LDA(At, 0, 1); PG8_STAGE(PG8_SB(0, 0), b2, voffB); PG8_STAGE(PG8_SB(0, 1), b2 + hstep, voffB); PG8_STAGE(PG8_SA(0, 0), a2, voffA);
;             PG8_WAIT_V(8); PG8_WAIT_L(0); PG8_BAR; PG8_MMA(1, 0, At, B0); PG8_MMA(1, 1, At, B1); PG8_BAR; PG8_SCHED;
.LBB0_174:
	s_add_u32 s42, s20, 0xfff80080
	s_addc_u32 s43, s21, -1
	s_add_i32 s76, 0, 0x10000
	s_cmp_eq_u32 s75, 28
	s_cselect_b32 s45, s15, s43
	s_cselect_b32 s44, s41, s42
	s_cselect_b32 s43, s13, s74
	s_cselect_b32 s42, s72, s73
	s_add_i32 s79, 0, 0x14000
	s_add_i32 m0, s56, 0xc000
	s_nop 0
	global_load_lds_dwordx4 v138, s[20:21]
	ds_read_b128 v[142:145], v230
	ds_read_b128 v[146:149], v230 offset:1024
	ds_read_b128 v[150:153], v230 offset:2048
	ds_read_b128 v[154:157], v230 offset:3072
	ds_read_b128 v[158:161], v230 offset:16384
	ds_read_b128 v[162:165], v230 offset:17408
	ds_read_b128 v[166:169], v230 offset:18432
	ds_read_b128 v[178:181], v230 offset:19456
	s_add_i32 m0, s56, 0xe000
	s_nop 0
	global_load_lds_dwordx4 v140, s[20:21]
	ds_read_b128 v[182:185], v175
	ds_read_b128 v[186:189], v175 offset:1024
	ds_read_b128 v[190:193], v175 offset:2048
	ds_read_b128 v[206:209], v175 offset:3072
	ds_read_b128 v[210:213], v175 offset:4096
	ds_read_b128 v[214:217], v175 offset:5120
	ds_read_b128 v[226:229], v175 offset:6144
	ds_read_b128 v[234:237], v175 offset:7168
	s_cmp_lg_u32 s10, 0
	s_cbranch_scc1 .Lh0w_g1_1
	s_waitcnt vmcnt(8)
.Lh0w_g1_1:
	s_waitcnt lgkmcnt(0)
	s_barrier
	s_setprio 1
	s_waitcnt lgkmcnt(0)
	v_mfma_f32_16x16x32_bf16 v[126:129], v[142:145], v[182:185], v[126:129]
	v_mfma_f32_16x16x32_bf16 v[118:121], v[150:153], v[182:185], v[118:121]
	v_mfma_f32_16x16x32_bf16 v[110:113], v[142:145], v[190:193], v[110:113]
	v_mfma_f32_16x16x32_bf16 v[102:105], v[150:153], v[190:193], v[102:105]
	v_mfma_f32_16x16x32_bf16 v[94:97], v[142:145], v[210:213], v[94:97]
	v_mfma_f32_16x16x32_bf16 v[86:89], v[150:153], v[210:213], v[86:89]
	v_mfma_f32_16x16x32_bf16 v[78:81], v[142:145], v[226:229], v[78:81]
	v_mfma_f32_16x16x32_bf16 v[70:73], v[150:153], v[226:229], v[70:73]
	v_mfma_f32_16x16x32_bf16 v[126:129], v[146:149], v[186:189], v[126:129]
	v_mfma_f32_16x16x32_bf16 v[118:121], v[154:157], v[186:189], v[118:121]
	v_mfma_f32_16x16x32_bf16 v[110:113], v[146:149], v[206:209], v[110:113]
	v_mfma_f32_16x16x32_bf16 v[102:105], v[154:157], v[206:209], v[102:105]
	v_mfma_f32_16x16x32_bf16 v[94:97], v[146:149], v[214:217], v[94:97]
	v_mfma_f32_16x16x32_bf16 v[86:89], v[154:157], v[214:217], v[86:89]
	v_mfma_f32_16x16x32_bf16 v[78:81], v[146:149], v[234:237], v[78:81]
	v_mfma_f32_16x16x32_bf16 v[70:73], v[154:157], v[234:237], v[70:73]
	s_setprio 0
	s_setprio 1
	v_mfma_f32_16x16x32_bf16 v[122:125], v[158:161], v[182:185], v[122:125]
	v_mfma_f32_16x16x32_bf16 v[114:117], v[166:169], v[182:185], v[114:117]
	v_mfma_f32_16x16x32_bf16 v[106:109], v[158:161], v[190:193], v[106:109]
	v_mfma_f32_16x16x32_bf16 v[98:101], v[166:169], v[190:193], v[98:101]
	v_mfma_f32_16x16x32_bf16 v[90:93], v[158:161], v[210:213], v[90:93]
	v_mfma_f32_16x16x32_bf16 v[82:85], v[166:169], v[210:213], v[82:85]
	v_mfma_f32_16x16x32_bf16 v[74:77], v[158:161], v[226:229], v[74:77]
	v_mfma_f32_16x16x32_bf16 v[66:69], v[166:169], v[226:229], v[66:69]
	v_mfma_f32_16x16x32_bf16 v[122:125], v[162:165], v[186:189], v[122:125]
	v_mfma_f32_16x16x32_bf16 v[114:117], v[178:181], v[186:189], v[114:117]
	v_mfma_f32_16x16x32_bf16 v[106:109], v[162:165], v[206:209], v[106:109]
	v_mfma_f32_16x16x32_bf16 v[98:101], v[178:181], v[206:209], v[98:101]
	v_mfma_f32_16x16x32_bf16 v[90:93], v[162:165], v[214:217], v[90:93]
	v_mfma_f32_16x16x32_bf16 v[82:85], v[178:181], v[214:217], v[82:85]
	v_mfma_f32_16x16x32_bf16 v[74:77], v[162:165], v[234:237], v[74:77]
	v_mfma_f32_16x16x32_bf16 v[66:69], v[178:181], v[234:237], v[66:69]
	s_setprio 0
	s_waitcnt vmcnt(8)
	s_barrier
	s_add_i32 s76, s76, s53
	s_mov_b32 m0, s76
	s_nop 0
	global_load_lds_dwordx4 v132, s[42:43]
	ds_read_b128 v[182:185], v175 offset:16384
	ds_read_b128 v[186:189], v175 offset:17408
	s_add_i32 m0, s76, 0x2000
	s_add_u32 s76, s42, 0x80000
	s_addc_u32 s77, s43, 0
	s_add_i32 s79, s79, s53
	global_load_lds_dwordx4 v136, s[42:43]
	ds_read_b128 v[190:193], v175 offset:18432
	ds_read_b128 v[206:209], v175 offset:19456
	s_mov_b32 m0, s79
	s_nop 0
	global_load_lds_dwordx4 v132, s[76:77]
	ds_read_b128 v[210:213], v175 offset:20480
	ds_read_b128 v[214:217], v175 offset:21504
	s_add_i32 m0, s79, 0x2000
	s_nop 0
	global_load_lds_dwordx4 v136, s[76:77]
	ds_read_b128 v[226:229], v175 offset:22528
	ds_read_b128 v[234:237], v175 offset:23552
	s_mov_b32 m0, s56
	s_nop 0
	global_load_lds_dwordx4 v130, s[44:45]
	s_mov_b32 m0, s57
	s_nop 0
	global_load_lds_dwordx4 v134, s[44:45]
	s_cmp_lg_u32 s10, 0
	s_cbranch_scc1 .Lh0w_g1_2
	s_waitcnt vmcnt(8)
; #define PG8_STAGE(bufoff, gbase, voff) do { _Pragma("unroll") for (int _i = 0; _i < 2; ++_i) \
;         __builtin_amdgcn_global_load_lds((const unsigned*)((const char*)(gbase) + (voff)[_i]), (PG8_LAS unsigned*)(lds + (bufoff) + ldsw + _i * 8192), 16, 0, 0); } while (0)
; #define PG8_LDA(dst, b, h) do { _Pragma("unroll") for (int m = 0; m < 4; ++m) _Pragma("unroll") for (int k = 0; k < 2; ++k) dst[m][k] = *(const PG8_LAS bf16x8*)(lds + PG8_SA(b, h) + aoff + m * 2048 + k * 1024); } while (0)
; #define PG8_LDB(dst, b, h) do { _Pragma("unroll") for (int n = 0; n < 2; ++n) _Pragma("unroll") for (int k = 0; k < 2; ++k) dst[n][k] = *(const PG8_LAS bf16x8*)(lds + PG8_SB(b, h) + boff + n * 2048 + k * 1024); } while (0)
; #define PG8_MMA(ai, bj, At, Bt) do { __builtin_amdgcn_s_setprio(1); _Pragma("unroll") for (int m = 0; m < 4; ++m) _Pragma("unroll") for (int n = 0; n < 2; ++n) _Pragma("unroll") for (int k = 0; k < 2; ++k) \
;         acc[ai][bj][m][n] = __builtin_amdgcn_mfma_f32_16x16x32_bf16(Bt[n][k], At[m][k], acc[ai][bj][m][n], 0, 0, 0); __builtin_amdgcn_s_setprio(0); } while (0)
; #define PG8_WAIT_V(n) asm volatile("s_waitcnt vmcnt(" #n ")" ::: "memory")
; #define PG8_WAIT_L(n) asm volatile("s_waitcnt lgkmcnt(" #n ")" ::: "memory")
; #define PG8_BAR __builtin_amdgcn_s_barrier()
; #define PG8_SCHED __builtin_amdgcn_sched_barrier(0)
; template <class Epi, class Sched, bool ALIGN_EPI = false, bool SP2 = false>
; __device__ __forceinline__ void gemm_phase(PG8_LAS unsigned char* lds, const Gemm g, const Sched& S, const Epi& E, const int wave_id) {
;     ...
;             PG8_WAIT_V(8); PG8_WAIT_L(0); PG8_BAR; PG8_MMA(1, 0, At, B0); PG8_MMA(1, 1, At, B1); PG8_BAR; PG8_SCHED;
;             PG8_LDB(B0, 1, 0); PG8_LDB(B1, 1, 1); PG8_SCHED; PG8_LDA(At, 1, 0); PG8_STAGE(PG8_SA(0, 1), a2 + hstep, voffA);
.Lh0w_g1_2:
	s_waitcnt lgkmcnt(0)
	s_barrier
	s_setprio 1
	s_waitcnt lgkmcnt(0)
	v_mfma_f32_16x16x32_bf16 v[62:65], v[142:145], v[182:185], v[62:65]
	v_mfma_f32_16x16x32_bf16 v[54:57], v[150:153], v[182:185], v[54:57]
	v_mfma_f32_16x16x32_bf16 v[46:49], v[142:145], v[190:193], v[46:49]
	v_mfma_f32_16x16x32_bf16 v[38:41], v[150:153], v[190:193], v[38:41]
	v_mfma_f32_16x16x32_bf16 v[30:33], v[142:145], v[210:213], v[30:33]
	v_mfma_f32_16x16x32_bf16 v[22:25], v[150:153], v[210:213], v[22:25]
	v_mfma_f32_16x16x32_bf16 v[14:17], v[142:145], v[226:229], v[14:17]
	v_mfma_f32_16x16x32_bf16 v[6:9], v[150:153], v[226:229], v[6:9]
	v_mfma_f32_16x16x32_bf16 v[62:65], v[146:149], v[186:189], v[62:65]
	v_mfma_f32_16x16x32_bf16 v[54:57], v[154:157], v[186:189], v[54:57]
	v_mfma_f32_16x16x32_bf16 v[46:49], v[146:149], v[206:209], v[46:49]
	v_mfma_f32_16x16x32_bf16 v[38:41], v[154:157], v[206:209], v[38:41]
	v_mfma_f32_16x16x32_bf16 v[30:33], v[146:149], v[214:217], v[30:33]
	v_mfma_f32_16x16x32_bf16 v[22:25], v[154:157], v[214:217], v[22:25]
	v_mfma_f32_16x16x32_bf16 v[14:17], v[146:149], v[234:237], v[14:17]
	v_mfma_f32_16x16x32_bf16 v[6:9], v[154:157], v[234:237], v[6:9]
	s_setprio 0
	s_setprio 1
	v_mfma_f32_16x16x32_bf16 v[58:61], v[158:161], v[182:185], v[58:61]
	v_mfma_f32_16x16x32_bf16 v[50:53], v[166:169], v[182:185], v[50:53]
	v_mfma_f32_16x16x32_bf16 v[42:45], v[158:161], v[190:193], v[42:45]
	v_mfma_f32_16x16x32_bf16 v[34:37], v[166:169], v[190:193], v[34:37]
	v_mfma_f32_16x16x32_bf16 v[26:29], v[158:161], v[210:213], v[26:29]
	v_mfma_f32_16x16x32_bf16 v[18:21], v[166:169], v[210:213], v[18:21]
	v_mfma_f32_16x16x32_bf16 v[10:13], v[158:161], v[226:229], v[10:13]
	v_mfma_f32_16x16x32_bf16 v[2:5], v[166:169], v[226:229], v[2:5]
	v_mfma_f32_16x16x32_bf16 v[58:61], v[162:165], v[186:189], v[58:61]
	v_mfma_f32_16x16x32_bf16 v[50:53], v[178:181], v[186:189], v[50:53]
	v_mfma_f32_16x16x32_bf16 v[42:45], v[162:165], v[206:209], v[42:45]
	v_mfma_f32_16x16x32_bf16 v[34:37], v[178:181], v[206:209], v[34:37]
	v_mfma_f32_16x16x32_bf16 v[26:29], v[162:165], v[214:217], v[26:29]
	v_mfma_f32_16x16x32_bf16 v[18:21], v[178:181], v[214:217], v[18:21]
	v_mfma_f32_16x16x32_bf16 v[10:13], v[162:165], v[234:237], v[10:13]
	v_mfma_f32_16x16x32_bf16 v[2:5], v[178:181], v[234:237], v[2:5]
	s_setprio 0
	s_waitcnt vmcnt(8)
	s_barrier
	s_add_i32 s76, 0, 0x18000
	s_add_i32 s77, 0, 0x1c000
	s_add_u32 s44, s44, 0x80000
	s_addc_u32 s45, s45, 0
	s_mov_b32 m0, s64
	s_nop 0
	global_load_lds_dwordx4 v130, s[44:45]
	ds_read_b128 v[142:145], v230 offset:32768
	ds_read_b128 v[146:149], v230 offset:33792
	ds_read_b128 v[150:153], v230 offset:34816
	ds_read_b128 v[154:157], v230 offset:35840
	ds_read_b128 v[158:161], v230 offset:49152
	ds_read_b128 v[162:165], v230 offset:50176
	ds_read_b128 v[166:169], v230 offset:51200
	ds_read_b128 v[178:181], v230 offset:52224
	s_mov_b32 m0, s65
	s_nop 0
	global_load_lds_dwordx4 v134, s[44:45]
	ds_read_b128 v[182:185], v175 offset:32768
	ds_read_b128 v[186:189], v175 offset:33792
	ds_read_b128 v[190:193], v175 offset:34816
	ds_read_b128 v[206:209], v175 offset:35840
	ds_read_b128 v[210:213], v175 offset:36864
	ds_read_b128 v[214:217], v175 offset:37888
	ds_read_b128 v[226:229], v175 offset:38912
	ds_read_b128 v[234:237], v175 offset:39936
	s_cmp_lg_u32 s10, 0
	s_cbranch_scc1 .Lh0w_g1_3
	s_waitcnt vmcnt(8)
; #define PG8_STAGE(bufoff, gbase, voff) do { _Pragma("unroll") for (int _i = 0; _i < 2; ++_i) \
;         __builtin_amdgcn_global_load_lds((const unsigned*)((const char*)(gbase) + (voff)[_i]), (PG8_LAS unsigned*)(lds + (bufoff) + ldsw + _i * 8192), 16, 0, 0); } while (0)
; #define PG8_LDA(dst, b, h) do { _Pragma("unroll") for (int m = 0; m < 4; ++m) _Pragma("unroll") for (int k = 0; k < 2; ++k) dst[m][k] = *(const PG8_LAS bf16x8*)(lds + PG8_SA(b, h) + aoff + m * 2048 + k * 1024); } while (0)
; #define PG8_MMA(ai, bj, At, Bt) do { __builtin_amdgcn_s_setprio(1); _Pragma("unroll") for (int m = 0; m < 4; ++m) _Pragma("unroll") for (int n = 0; n < 2; ++n) _Pragma("unroll") for (int k = 0; k < 2; ++k) \
;         acc[ai][bj][m][n] = __builtin_amdgcn_mfma_f32_16x16x32_bf16(Bt[n][k], At[m][k], acc[ai][bj][m][n], 0, 0, 0); __builtin_amdgcn_s_setprio(0); } while (0)
; #define PG8_WAIT_V(n) asm volatile("s_waitcnt vmcnt(" #n ")" ::: "memory")
; #define PG8_WAIT_L(n) asm volatile("s_waitcnt lgkmcnt(" #n ")" ::: "memory")
; #define PG8_BAR __builtin_amdgcn_s_barrier()
; #define PG8_SCHED __builtin_amdgcn_sched_barrier(0)
; template <class Epi, class Sched, bool ALIGN_EPI = false, bool SP2 = false>
; __device__ __forceinline__ void gemm_phase(PG8_LAS unsigned char* lds, const Gemm g, const Sched& S, const Epi& E, const int wave_id) {
;     ...
;             PG8_WAIT_V(8); PG8_WAIT_L(0); PG8_BAR; PG8_MMA(0, 0, At, B0); PG8_MMA(0, 1, At, B1); PG8_BAR; PG8_SCHED;
;             PG8_LDA(At, 1, 1); PG8_STAGE(PG8_SB(1, 0), b3, voffB); PG8_STAGE(PG8_SB(1, 1), b3 + hstep, voffB); PG8_STAGE(PG8_SA(1, 0), a3, voffA);
;             PG8_WAIT_V(8); PG8_WAIT_L(0); PG8_BAR; PG8_MMA(1, 0, At, B0); PG8_MMA(1, 1, At, B1); PG8_BAR; PG8_SCHED;
.Lh0w_g1_3:
	s_waitcnt lgkmcnt(0)
	s_barrier
	s_setprio 1
	s_waitcnt lgkmcnt(0)
	v_mfma_f32_16x16x32_bf16 v[126:129], v[142:145], v[182:185], v[126:129]
	v_mfma_f32_16x16x32_bf16 v[118:121], v[150:153], v[182:185], v[118:121]
	v_mfma_f32_16x16x32_bf16 v[110:113], v[142:145], v[190:193], v[110:113]
	v_mfma_f32_16x16x32_bf16 v[102:105], v[150:153], v[190:193], v[102:105]
	v_mfma_f32_16x16x32_bf16 v[94:97], v[142:145], v[210:213], v[94:97]
	v_mfma_f32_16x16x32_bf16 v[86:89], v[150:153], v[210:213], v[86:89]
	v_mfma_f32_16x16x32_bf16 v[78:81], v[142:145], v[226:229], v[78:81]
	v_mfma_f32_16x16x32_bf16 v[70:73], v[150:153], v[226:229], v[70:73]
	v_mfma_f32_16x16x32_bf16 v[126:129], v[146:149], v[186:189], v[126:129]
	v_mfma_f32_16x16x32_bf16 v[118:121], v[154:157], v[186:189], v[118:121]
	v_mfma_f32_16x16x32_bf16 v[110:113], v[146:149], v[206:209], v[110:113]
	v_mfma_f32_16x16x32_bf16 v[102:105], v[154:157], v[206:209], v[102:105]
	v_mfma_f32_16x16x32_bf16 v[94:97], v[146:149], v[214:217], v[94:97]
	v_mfma_f32_16x16x32_bf16 v[86:89], v[154:157], v[214:217], v[86:89]
	v_mfma_f32_16x16x32_bf16 v[78:81], v[146:149], v[234:237], v[78:81]
	v_mfma_f32_16x16x32_bf16 v[70:73], v[154:157], v[234:237], v[70:73]
	s_setprio 0
	s_setprio 1
	v_mfma_f32_16x16x32_bf16 v[122:125], v[158:161], v[182:185], v[122:125]
	v_mfma_f32_16x16x32_bf16 v[114:117], v[166:169], v[182:185], v[114:117]
	v_mfma_f32_16x16x32_bf16 v[106:109], v[158:161], v[190:193], v[106:109]
	v_mfma_f32_16x16x32_bf16 v[98:101], v[166:169], v[190:193], v[98:101]
	v_mfma_f32_16x16x32_bf16 v[90:93], v[158:161], v[210:213], v[90:93]
	v_mfma_f32_16x16x32_bf16 v[82:85], v[166:169], v[210:213], v[82:85]
	v_mfma_f32_16x16x32_bf16 v[74:77], v[158:161], v[226:229], v[74:77]
	v_mfma_f32_16x16x32_bf16 v[66:69], v[166:169], v[226:229], v[66:69]
	v_mfma_f32_16x16x32_bf16 v[122:125], v[162:165], v[186:189], v[122:125]
	v_mfma_f32_16x16x32_bf16 v[114:117], v[178:181], v[186:189], v[114:117]
	v_mfma_f32_16x16x32_bf16 v[106:109], v[162:165], v[206:209], v[106:109]
	v_mfma_f32_16x16x32_bf16 v[98:101], v[178:181], v[206:209], v[98:101]
	v_mfma_f32_16x16x32_bf16 v[90:93], v[162:165], v[214:217], v[90:93]
	v_mfma_f32_16x16x32_bf16 v[82:85], v[178:181], v[214:217], v[82:85]
	v_mfma_f32_16x16x32_bf16 v[74:77], v[162:165], v[234:237], v[74:77]
	v_mfma_f32_16x16x32_bf16 v[66:69], v[178:181], v[234:237], v[66:69]
	s_setprio 0
	s_waitcnt vmcnt(8)
	s_barrier
	s_add_u32 vcc_lo, s44, 0xfff80080
	s_addc_u32 vcc_hi, s45, -1
	s_mov_b32 m0, s68
	s_nop 0
	global_load_lds_dwordx4 v130, vcc
	ds_read_b128 v[182:185], v175 offset:49152
	ds_read_b128 v[186:189], v175 offset:50176
	s_mov_b32 m0, s69
	s_add_i32 s44, s76, s53
	global_load_lds_dwordx4 v134, vcc
	ds_read_b128 v[190:193], v175 offset:51200
	ds_read_b128 v[206:209], v175 offset:52224
	s_add_u32 vcc_lo, s42, 0x80
	s_addc_u32 vcc_hi, s43, 0
	s_mov_b32 m0, s44
	s_nop 0
	global_load_lds_dwordx4 v132, vcc
	ds_read_b128 v[210:213], v175 offset:53248
	ds_read_b128 v[214:217], v175 offset:54272
	s_add_i32 m0, s44, 0x2000
	s_add_u32 s42, s42, 0x80080
	s_addc_u32 s43, s43, 0
	global_load_lds_dwordx4 v136, vcc
	ds_read_b128 v[226:229], v175 offset:55296
	ds_read_b128 v[234:237], v175 offset:56320
	s_add_i32 s44, s77, s53
	s_mov_b32 m0, s44
	s_nop 0
	global_load_lds_dwordx4 v132, s[42:43]
	s_add_i32 m0, s44, 0x2000
	s_nop 0
	global_load_lds_dwordx4 v136, s[42:43]
	s_cmp_lg_u32 s10, 0
	s_cbranch_scc1 .Lh0w_g1_4
	s_waitcnt vmcnt(8)
.Lh0w_g1_4:
	s_waitcnt lgkmcnt(0)
	s_barrier
	s_setprio 1
	s_waitcnt lgkmcnt(0)
	v_mfma_f32_16x16x32_bf16 v[62:65], v[142:145], v[182:185], v[62:65]
	v_mfma_f32_16x16x32_bf16 v[54:57], v[150:153], v[182:185], v[54:57]
	v_mfma_f32_16x16x32_bf16 v[46:49], v[142:145], v[190:193], v[46:49]
	v_mfma_f32_16x16x32_bf16 v[38:41], v[150:153], v[190:193], v[38:41]
	v_mfma_f32_16x16x32_bf16 v[30:33], v[142:145], v[210:213], v[30:33]
	v_mfma_f32_16x16x32_bf16 v[22:25], v[150:153], v[210:213], v[22:25]
	v_mfma_f32_16x16x32_bf16 v[14:17], v[142:145], v[226:229], v[14:17]
	v_mfma_f32_16x16x32_bf16 v[6:9], v[150:153], v[226:229], v[6:9]
	v_mfma_f32_16x16x32_bf16 v[62:65], v[146:149], v[186:189], v[62:65]
	v_mfma_f32_16x16x32_bf16 v[54:57], v[154:157], v[186:189], v[54:57]
	v_mfma_f32_16x16x32_bf16 v[46:49], v[146:149], v[206:209], v[46:49]
	v_mfma_f32_16x16x32_bf16 v[38:41], v[154:157], v[206:209], v[38:41]
	v_mfma_f32_16x16x32_bf16 v[30:33], v[146:149], v[214:217], v[30:33]
	v_mfma_f32_16x16x32_bf16 v[22:25], v[154:157], v[214:217], v[22:25]
	v_mfma_f32_16x16x32_bf16 v[14:17], v[146:149], v[234:237], v[14:17]
	v_mfma_f32_16x16x32_bf16 v[6:9], v[154:157], v[234:237], v[6:9]
	s_setprio 0
	s_setprio 1
	v_mfma_f32_16x16x32_bf16 v[58:61], v[158:161], v[182:185], v[58:61]
	v_mfma_f32_16x16x32_bf16 v[50:53], v[166:169], v[182:185], v[50:53]
	v_mfma_f32_16x16x32_bf16 v[42:45], v[158:161], v[190:193], v[42:45]
	v_mfma_f32_16x16x32_bf16 v[34:37], v[166:169], v[190:193], v[34:37]
	v_mfma_f32_16x16x32_bf16 v[26:29], v[158:161], v[210:213], v[26:29]
	v_mfma_f32_16x16x32_bf16 v[18:21], v[166:169], v[210:213], v[18:21]
	v_mfma_f32_16x16x32_bf16 v[10:13], v[158:161], v[226:229], v[10:13]
	v_mfma_f32_16x16x32_bf16 v[2:5], v[166:169], v[226:229], v[2:5]
	v_mfma_f32_16x16x32_bf16 v[58:61], v[162:165], v[186:189], v[58:61]
	v_mfma_f32_16x16x32_bf16 v[50:53], v[178:181], v[186:189], v[50:53]
	v_mfma_f32_16x16x32_bf16 v[42:45], v[162:165], v[206:209], v[42:45]
	v_mfma_f32_16x16x32_bf16 v[34:37], v[178:181], v[206:209], v[34:37]
	v_mfma_f32_16x16x32_bf16 v[26:29], v[162:165], v[214:217], v[26:29]
	v_mfma_f32_16x16x32_bf16 v[18:21], v[178:181], v[214:217], v[18:21]
	v_mfma_f32_16x16x32_bf16 v[10:13], v[162:165], v[234:237], v[10:13]
	v_mfma_f32_16x16x32_bf16 v[2:5], v[178:181], v[234:237], v[2:5]
	s_setprio 0
	s_waitcnt vmcnt(8)
	s_barrier
	s_add_i32 s75, s75, 2
	s_add_u32 s20, s20, 0x100
	s_addc_u32 s21, s21, 0
	s_add_u32 s73, s73, 0x100
	s_addc_u32 s74, s74, 0
	s_cmp_gt_u32 s75, 29
	s_cbranch_scc0 .LBB0_174
	s_and_b64 vcc, exec, s[10:11]
	s_cbranch_vccz .LBB0_177
	s_barrier

; #define PG8_STAGE(bufoff, gbase, voff) do { _Pragma("unroll") for (int _i = 0; _i < 2; ++_i) \
;         __builtin_amdgcn_global_load_lds((const unsigned*)((const char*)(gbase) + (voff)[_i]), (PG8_LAS unsigned*)(lds + (bufoff) + ldsw + _i * 8192), 16, 0, 0); } while (0)
; #define PG8_LDA(dst, b, h) do { _Pragma("unroll") for (int m = 0; m < 4; ++m) _Pragma("unroll") for (int k = 0; k < 2; ++k) dst[m][k] = *(const PG8_LAS bf16x8*)(lds + PG8_SA(b, h) + aoff + m * 2048 + k * 1024); } while (0)
; #define PG8_LDB(dst, b, h) do { _Pragma("unroll") for (int n = 0; n < 2; ++n) _Pragma("unroll") for (int k = 0; k < 2; ++k) dst[n][k] = *(const PG8_LAS bf16x8*)(lds + PG8_SB(b, h) + boff + n * 2048 + k * 1024); } while (0)
; #define PG8_MMA(ai, bj, At, Bt) do { __builtin_amdgcn_s_setprio(1); _Pragma("unroll") for (int m = 0; m < 4; ++m) _Pragma("unroll") for (int n = 0; n < 2; ++n) _Pragma("unroll") for (int k = 0; k < 2; ++k) \
;         acc[ai][bj][m][n] = __builtin_amdgcn_mfma_f32_16x16x32_bf16(Bt[n][k], At[m][k], acc[ai][bj][m][n], 0, 0, 0); __builtin_amdgcn_s_setprio(0); } while (0)
; #define PG8_WAIT_V(n) asm volatile("s_waitcnt vmcnt(" #n ")" ::: "memory")
; #define PG8_WAIT_L(n) asm volatile("s_waitcnt lgkmcnt(" #n ")" ::: "memory")
; #define PG8_BAR __builtin_amdgcn_s_barrier()
; #define PG8_SCHED __builtin_amdgcn_sched_barrier(0)
; template <class Epi, class Sched, bool ALIGN_EPI = false, bool SP2 = false>
; __device__ __forceinline__ void gemm_phase(PG8_LAS unsigned char* lds, const Gemm g, const Sched& S, const Epi& E, const int wave_id) {
;     ...
;             PG8_LDB(B0, 0, 0); PG8_LDB(B1, 0, 1); PG8_SCHED; PG8_LDA(At, 0, 0); PG8_STAGE(PG8_SA(1, 1), a1 + hstep, voffA);
;             PG8_WAIT_V(8); PG8_WAIT_L(0); PG8_BAR; PG8_MMA(0, 0, At, B0); PG8_MMA(0, 1, At, B1); PG8_BAR; PG8_SCHED;
;             PG8_LDA(At, 0, 1); PG8_STAGE(PG8_SB(0, 0), b2, voffB); PG8_STAGE(PG8_SB(0, 1), b2 + hstep, voffB); PG8_STAGE(PG8_SA(0, 0), a2, voffA);
;             PG8_WAIT_V(8); PG8_WAIT_L(0); PG8_BAR; PG8_MMA(1, 0, At, B0); PG8_MMA(1, 1, At, B1); PG8_BAR; PG8_SCHED;
.LBB0_524:
	s_add_u32 s42, s40, 0xfff80080
	s_addc_u32 s43, s41, -1
	s_add_i32 s77, 0, 0x10000
	s_cmp_eq_u32 s76, 28
	s_cselect_b32 s45, s15, s43
	s_cselect_b32 s44, s21, s42
	s_cselect_b32 s43, s13, s75
	s_cselect_b32 s42, s73, s74
	s_add_i32 s79, 0, 0x14000
	s_add_i32 m0, s56, 0xc000
	s_nop 0
	global_load_lds_dwordx4 v210, s[40:41]
	ds_read_b128 v[118:121], v226
	ds_read_b128 v[122:125], v226 offset:1024
	ds_read_b128 v[130:133], v226 offset:2048
	ds_read_b128 v[134:137], v226 offset:3072
	ds_read_b128 v[146:149], v226 offset:16384
	ds_read_b128 v[150:153], v226 offset:17408
	ds_read_b128 v[154:157], v226 offset:18432
	ds_read_b128 v[158:161], v226 offset:19456
	s_add_i32 m0, s56, 0xe000
	s_nop 0
	global_load_lds_dwordx4 v212, s[40:41]
	ds_read_b128 v[162:165], v222
	ds_read_b128 v[166:169], v222 offset:1024
	ds_read_b128 v[170:173], v222 offset:2048
	ds_read_b128 v[174:177], v222 offset:3072
	ds_read_b128 v[178:181], v222 offset:4096
	ds_read_b128 v[182:185], v222 offset:5120
	ds_read_b128 v[186:189], v222 offset:6144
	ds_read_b128 v[214:217], v222 offset:7168
	s_cmp_lg_u32 s10, 0
	s_cbranch_scc1 .Lh0w_g2_1
	s_waitcnt vmcnt(8)
.Lh0w_g2_1:
	s_waitcnt lgkmcnt(0)
	s_barrier
	s_setprio 1
	s_waitcnt lgkmcnt(0)
	v_mfma_f32_16x16x32_bf16 v[142:145], v[118:121], v[162:165], v[142:145]
	v_mfma_f32_16x16x32_bf16 v[138:141], v[130:133], v[162:165], v[138:141]
	v_mfma_f32_16x16x32_bf16 v[110:113], v[118:121], v[170:173], v[110:113]
	v_mfma_f32_16x16x32_bf16 v[106:109], v[130:133], v[170:173], v[106:109]
	v_mfma_f32_16x16x32_bf16 v[94:97], v[118:121], v[178:181], v[94:97]
	v_mfma_f32_16x16x32_bf16 v[90:93], v[130:133], v[178:181], v[90:93]
	v_mfma_f32_16x16x32_bf16 v[78:81], v[118:121], v[186:189], v[78:81]
	v_mfma_f32_16x16x32_bf16 v[74:77], v[130:133], v[186:189], v[74:77]
	v_mfma_f32_16x16x32_bf16 v[142:145], v[122:125], v[166:169], v[142:145]
	v_mfma_f32_16x16x32_bf16 v[138:141], v[134:137], v[166:169], v[138:141]
	v_mfma_f32_16x16x32_bf16 v[110:113], v[122:125], v[174:177], v[110:113]
	v_mfma_f32_16x16x32_bf16 v[106:109], v[134:137], v[174:177], v[106:109]
	v_mfma_f32_16x16x32_bf16 v[94:97], v[122:125], v[182:185], v[94:97]
	v_mfma_f32_16x16x32_bf16 v[90:93], v[134:137], v[182:185], v[90:93]
	v_mfma_f32_16x16x32_bf16 v[78:81], v[122:125], v[214:217], v[78:81]
	v_mfma_f32_16x16x32_bf16 v[74:77], v[134:137], v[214:217], v[74:77]
	s_setprio 0
	s_setprio 1
	v_mfma_f32_16x16x32_bf16 v[126:129], v[146:149], v[162:165], v[126:129]
	v_mfma_f32_16x16x32_bf16 v[114:117], v[154:157], v[162:165], v[114:117]
	v_mfma_f32_16x16x32_bf16 v[102:105], v[146:149], v[170:173], v[102:105]
	v_mfma_f32_16x16x32_bf16 v[98:101], v[154:157], v[170:173], v[98:101]
	v_mfma_f32_16x16x32_bf16 v[86:89], v[146:149], v[178:181], v[86:89]
	v_mfma_f32_16x16x32_bf16 v[82:85], v[154:157], v[178:181], v[82:85]
	v_mfma_f32_16x16x32_bf16 v[70:73], v[146:149], v[186:189], v[70:73]
	v_mfma_f32_16x16x32_bf16 v[66:69], v[154:157], v[186:189], v[66:69]
	v_mfma_f32_16x16x32_bf16 v[126:129], v[150:153], v[166:169], v[126:129]
	v_mfma_f32_16x16x32_bf16 v[114:117], v[158:161], v[166:169], v[114:117]
	v_mfma_f32_16x16x32_bf16 v[102:105], v[150:153], v[174:177], v[102:105]
	v_mfma_f32_16x16x32_bf16 v[98:101], v[158:161], v[174:177], v[98:101]
	v_mfma_f32_16x16x32_bf16 v[86:89], v[150:153], v[182:185], v[86:89]
	v_mfma_f32_16x16x32_bf16 v[82:85], v[158:161], v[182:185], v[82:85]
	v_mfma_f32_16x16x32_bf16 v[70:73], v[150:153], v[214:217], v[70:73]
	v_mfma_f32_16x16x32_bf16 v[66:69], v[158:161], v[214:217], v[66:69]
	s_setprio 0
	s_waitcnt vmcnt(8)
	s_barrier
	s_add_i32 s77, s77, s53
	s_mov_b32 m0, s77
	s_nop 0
	global_load_lds_dwordx4 v192, s[42:43]
	ds_read_b128 v[162:165], v222 offset:16384
	ds_read_b128 v[166:169], v222 offset:17408
	s_add_i32 m0, s77, 0x2000
	s_add_u32 s80, s42, 0x80000
	s_addc_u32 s81, s43, 0
	s_add_i32 s77, s79, s53
	global_load_lds_dwordx4 v208, s[42:43]
	ds_read_b128 v[170:173], v222 offset:18432
	ds_read_b128 v[174:177], v222 offset:19456
	s_mov_b32 m0, s77
	s_nop 0
	global_load_lds_dwordx4 v192, s[80:81]
	ds_read_b128 v[178:181], v222 offset:20480
	ds_read_b128 v[182:185], v222 offset:21504
	s_add_i32 m0, s77, 0x2000
	s_nop 0
	global_load_lds_dwordx4 v208, s[80:81]
	ds_read_b128 v[186:189], v222 offset:22528
	ds_read_b128 v[214:217], v222 offset:23552
	s_mov_b32 m0, s56
	s_nop 0
	global_load_lds_dwordx4 v190, s[44:45]
	s_mov_b32 m0, s57
	s_nop 0
	global_load_lds_dwordx4 v206, s[44:45]
	s_cmp_lg_u32 s10, 0
	s_cbranch_scc1 .Lh0w_g2_2
	s_waitcnt vmcnt(8)
; #define PG8_STAGE(bufoff, gbase, voff) do { _Pragma("unroll") for (int _i = 0; _i < 2; ++_i) \
;         __builtin_amdgcn_global_load_lds((const unsigned*)((const char*)(gbase) + (voff)[_i]), (PG8_LAS unsigned*)(lds + (bufoff) + ldsw + _i * 8192), 16, 0, 0); } while (0)
; #define PG8_LDA(dst, b, h) do { _Pragma("unroll") for (int m = 0; m < 4; ++m) _Pragma("unroll") for (int k = 0; k < 2; ++k) dst[m][k] = *(const PG8_LAS bf16x8*)(lds + PG8_SA(b, h) + aoff + m * 2048 + k * 1024); } while (0)
; #define PG8_LDB(dst, b, h) do { _Pragma("unroll") for (int n = 0; n < 2; ++n) _Pragma("unroll") for (int k = 0; k < 2; ++k) dst[n][k] = *(const PG8_LAS bf16x8*)(lds + PG8_SB(b, h) + boff + n * 2048 + k * 1024); } while (0)
; #define PG8_MMA(ai, bj, At, Bt) do { __builtin_amdgcn_s_setprio(1); _Pragma("unroll") for (int m = 0; m < 4; ++m) _Pragma("unroll") for (int n = 0; n < 2; ++n) _Pragma("unroll") for (int k = 0; k < 2; ++k) \
;         acc[ai][bj][m][n] = __builtin_amdgcn_mfma_f32_16x16x32_bf16(Bt[n][k], At[m][k], acc[ai][bj][m][n], 0, 0, 0); __builtin_amdgcn_s_setprio(0); } while (0)
; #define PG8_WAIT_V(n) asm volatile("s_waitcnt vmcnt(" #n ")" ::: "memory")
; #define PG8_WAIT_L(n) asm volatile("s_waitcnt lgkmcnt(" #n ")" ::: "memory")
; #define PG8_BAR __builtin_amdgcn_s_barrier()
; #define PG8_SCHED __builtin_amdgcn_sched_barrier(0)
; template <class Epi, class Sched, bool ALIGN_EPI = false, bool SP2 = false>
; __device__ __forceinline__ void gemm_phase(PG8_LAS unsigned char* lds, const Gemm g, const Sched& S, const Epi& E, const int wave_id) {
;     ...
;             PG8_WAIT_V(8); PG8_WAIT_L(0); PG8_BAR; PG8_MMA(1, 0, At, B0); PG8_MMA(1, 1, At, B1); PG8_BAR; PG8_SCHED;
;             PG8_LDB(B0, 1, 0); PG8_LDB(B1, 1, 1); PG8_SCHED; PG8_LDA(At, 1, 0); PG8_STAGE(PG8_SA(0, 1), a2 + hstep, voffA);
.Lh0w_g2_2:
	s_waitcnt lgkmcnt(0)
	s_barrier
	s_setprio 1
	s_waitcnt lgkmcnt(0)
	v_mfma_f32_16x16x32_bf16 v[62:65], v[118:121], v[162:165], v[62:65]
	v_mfma_f32_16x16x32_bf16 v[58:61], v[130:133], v[162:165], v[58:61]
	v_mfma_f32_16x16x32_bf16 v[46:49], v[118:121], v[170:173], v[46:49]
	v_mfma_f32_16x16x32_bf16 v[42:45], v[130:133], v[170:173], v[42:45]
	v_mfma_f32_16x16x32_bf16 v[30:33], v[118:121], v[178:181], v[30:33]
	v_mfma_f32_16x16x32_bf16 v[26:29], v[130:133], v[178:181], v[26:29]
	v_mfma_f32_16x16x32_bf16 v[14:17], v[118:121], v[186:189], v[14:17]
	v_mfma_f32_16x16x32_bf16 v[10:13], v[130:133], v[186:189], v[10:13]
	v_mfma_f32_16x16x32_bf16 v[62:65], v[122:125], v[166:169], v[62:65]
	v_mfma_f32_16x16x32_bf16 v[58:61], v[134:137], v[166:169], v[58:61]
	v_mfma_f32_16x16x32_bf16 v[46:49], v[122:125], v[174:177], v[46:49]
	v_mfma_f32_16x16x32_bf16 v[42:45], v[134:137], v[174:177], v[42:45]
	v_mfma_f32_16x16x32_bf16 v[30:33], v[122:125], v[182:185], v[30:33]
	v_mfma_f32_16x16x32_bf16 v[26:29], v[134:137], v[182:185], v[26:29]
	v_mfma_f32_16x16x32_bf16 v[14:17], v[122:125], v[214:217], v[14:17]
	v_mfma_f32_16x16x32_bf16 v[10:13], v[134:137], v[214:217], v[10:13]
	s_setprio 0
	s_setprio 1
	v_mfma_f32_16x16x32_bf16 v[54:57], v[146:149], v[162:165], v[54:57]
	v_mfma_f32_16x16x32_bf16 v[50:53], v[154:157], v[162:165], v[50:53]
	v_mfma_f32_16x16x32_bf16 v[38:41], v[146:149], v[170:173], v[38:41]
	v_mfma_f32_16x16x32_bf16 v[34:37], v[154:157], v[170:173], v[34:37]
	v_mfma_f32_16x16x32_bf16 v[22:25], v[146:149], v[178:181], v[22:25]
	v_mfma_f32_16x16x32_bf16 v[18:21], v[154:157], v[178:181], v[18:21]
	v_mfma_f32_16x16x32_bf16 v[6:9], v[146:149], v[186:189], v[6:9]
	v_mfma_f32_16x16x32_bf16 v[2:5], v[154:157], v[186:189], v[2:5]
	v_mfma_f32_16x16x32_bf16 v[54:57], v[150:153], v[166:169], v[54:57]
	v_mfma_f32_16x16x32_bf16 v[50:53], v[158:161], v[166:169], v[50:53]
	v_mfma_f32_16x16x32_bf16 v[38:41], v[150:153], v[174:177], v[38:41]
	v_mfma_f32_16x16x32_bf16 v[34:37], v[158:161], v[174:177], v[34:37]
	v_mfma_f32_16x16x32_bf16 v[22:25], v[150:153], v[182:185], v[22:25]
	v_mfma_f32_16x16x32_bf16 v[18:21], v[158:161], v[182:185], v[18:21]
	v_mfma_f32_16x16x32_bf16 v[6:9], v[150:153], v[214:217], v[6:9]
	v_mfma_f32_16x16x32_bf16 v[2:5], v[158:161], v[214:217], v[2:5]
	s_setprio 0
	s_waitcnt vmcnt(8)
	s_barrier
	s_add_i32 s77, 0, 0x18000
	s_add_i32 s79, 0, 0x1c000
	s_add_u32 s44, s44, 0x80000
	s_addc_u32 s45, s45, 0
	s_mov_b32 m0, s64
	s_nop 0
	global_load_lds_dwordx4 v190, s[44:45]
	ds_read_b128 v[118:121], v226 offset:32768
	ds_read_b128 v[122:125], v226 offset:33792
	ds_read_b128 v[130:133], v226 offset:34816
	ds_read_b128 v[134:137], v226 offset:35840
	ds_read_b128 v[146:149], v226 offset:49152
	ds_read_b128 v[150:153], v226 offset:50176
	ds_read_b128 v[154:157], v226 offset:51200
	ds_read_b128 v[158:161], v226 offset:52224
	s_mov_b32 m0, s65
	s_nop 0
	global_load_lds_dwordx4 v206, s[44:45]
	ds_read_b128 v[162:165], v222 offset:32768
	ds_read_b128 v[166:169], v222 offset:33792
	ds_read_b128 v[170:173], v222 offset:34816
	ds_read_b128 v[174:177], v222 offset:35840
	ds_read_b128 v[178:181], v222 offset:36864
	ds_read_b128 v[182:185], v222 offset:37888
	ds_read_b128 v[186:189], v222 offset:38912
	ds_read_b128 v[214:217], v222 offset:39936
	s_cmp_lg_u32 s10, 0
	s_cbranch_scc1 .Lh0w_g2_3
	s_waitcnt vmcnt(8)
; #define PG8_STAGE(bufoff, gbase, voff) do { _Pragma("unroll") for (int _i = 0; _i < 2; ++_i) \
;         __builtin_amdgcn_global_load_lds((const unsigned*)((const char*)(gbase) + (voff)[_i]), (PG8_LAS unsigned*)(lds + (bufoff) + ldsw + _i * 8192), 16, 0, 0); } while (0)
; #define PG8_LDA(dst, b, h) do { _Pragma("unroll") for (int m = 0; m < 4; ++m) _Pragma("unroll") for (int k = 0; k < 2; ++k) dst[m][k] = *(const PG8_LAS bf16x8*)(lds + PG8_SA(b, h) + aoff + m * 2048 + k * 1024); } while (0)
; #define PG8_MMA(ai, bj, At, Bt) do { __builtin_amdgcn_s_setprio(1); _Pragma("unroll") for (int m = 0; m < 4; ++m) _Pragma("unroll") for (int n = 0; n < 2; ++n) _Pragma("unroll") for (int k = 0; k < 2; ++k) \
;         acc[ai][bj][m][n] = __builtin_amdgcn_mfma_f32_16x16x32_bf16(Bt[n][k], At[m][k], acc[ai][bj][m][n], 0, 0, 0); __builtin_amdgcn_s_setprio(0); } while (0)
; #define PG8_WAIT_V(n) asm volatile("s_waitcnt vmcnt(" #n ")" ::: "memory")
; #define PG8_WAIT_L(n) asm volatile("s_waitcnt lgkmcnt(" #n ")" ::: "memory")
; #define PG8_BAR __builtin_amdgcn_s_barrier()
; #define PG8_SCHED __builtin_amdgcn_sched_barrier(0)
; template <class Epi, class Sched, bool ALIGN_EPI = false, bool SP2 = false>
; __device__ __forceinline__ void gemm_phase(PG8_LAS unsigned char* lds, const Gemm g, const Sched& S, const Epi& E, const int wave_id) {
;     ...
;             PG8_WAIT_V(8); PG8_WAIT_L(0); PG8_BAR; PG8_MMA(0, 0, At, B0); PG8_MMA(0, 1, At, B1); PG8_BAR; PG8_SCHED;
;             PG8_LDA(At, 1, 1); PG8_STAGE(PG8_SB(1, 0), b3, voffB); PG8_STAGE(PG8_SB(1, 1), b3 + hstep, voffB); PG8_STAGE(PG8_SA(1, 0), a3, voffA);
;             PG8_WAIT_V(8); PG8_WAIT_L(0); PG8_BAR; PG8_MMA(1, 0, At, B0); PG8_MMA(1, 1, At, B1); PG8_BAR; PG8_SCHED;
.Lh0w_g2_3:
	s_waitcnt lgkmcnt(0)
	s_barrier
	s_setprio 1
	s_waitcnt lgkmcnt(0)
	v_mfma_f32_16x16x32_bf16 v[142:145], v[118:121], v[162:165], v[142:145]
	v_mfma_f32_16x16x32_bf16 v[138:141], v[130:133], v[162:165], v[138:141]
	v_mfma_f32_16x16x32_bf16 v[110:113], v[118:121], v[170:173], v[110:113]
	v_mfma_f32_16x16x32_bf16 v[106:109], v[130:133], v[170:173], v[106:109]
	v_mfma_f32_16x16x32_bf16 v[94:97], v[118:121], v[178:181], v[94:97]
	v_mfma_f32_16x16x32_bf16 v[90:93], v[130:133], v[178:181], v[90:93]
	v_mfma_f32_16x16x32_bf16 v[78:81], v[118:121], v[186:189], v[78:81]
	v_mfma_f32_16x16x32_bf16 v[74:77], v[130:133], v[186:189], v[74:77]
	v_mfma_f32_16x16x32_bf16 v[142:145], v[122:125], v[166:169], v[142:145]
	v_mfma_f32_16x16x32_bf16 v[138:141], v[134:137], v[166:169], v[138:141]
	v_mfma_f32_16x16x32_bf16 v[110:113], v[122:125], v[174:177], v[110:113]
	v_mfma_f32_16x16x32_bf16 v[106:109], v[134:137], v[174:177], v[106:109]
	v_mfma_f32_16x16x32_bf16 v[94:97], v[122:125], v[182:185], v[94:97]
	v_mfma_f32_16x16x32_bf16 v[90:93], v[134:137], v[182:185], v[90:93]
	v_mfma_f32_16x16x32_bf16 v[78:81], v[122:125], v[214:217], v[78:81]
	v_mfma_f32_16x16x32_bf16 v[74:77], v[134:137], v[214:217], v[74:77]
	s_setprio 0
	s_setprio 1
	v_mfma_f32_16x16x32_bf16 v[126:129], v[146:149], v[162:165], v[126:129]
	v_mfma_f32_16x16x32_bf16 v[114:117], v[154:157], v[162:165], v[114:117]
	v_mfma_f32_16x16x32_bf16 v[102:105], v[146:149], v[170:173], v[102:105]
	v_mfma_f32_16x16x32_bf16 v[98:101], v[154:157], v[170:173], v[98:101]
	v_mfma_f32_16x16x32_bf16 v[86:89], v[146:149], v[178:181], v[86:89]
	v_mfma_f32_16x16x32_bf16 v[82:85], v[154:157], v[178:181], v[82:85]
	v_mfma_f32_16x16x32_bf16 v[70:73], v[146:149], v[186:189], v[70:73]
	v_mfma_f32_16x16x32_bf16 v[66:69], v[154:157], v[186:189], v[66:69]
	v_mfma_f32_16x16x32_bf16 v[126:129], v[150:153], v[166:169], v[126:129]
	v_mfma_f32_16x16x32_bf16 v[114:117], v[158:161], v[166:169], v[114:117]
	v_mfma_f32_16x16x32_bf16 v[102:105], v[150:153], v[174:177], v[102:105]
	v_mfma_f32_16x16x32_bf16 v[98:101], v[158:161], v[174:177], v[98:101]
	v_mfma_f32_16x16x32_bf16 v[86:89], v[150:153], v[182:185], v[86:89]
	v_mfma_f32_16x16x32_bf16 v[82:85], v[158:161], v[182:185], v[82:85]
	v_mfma_f32_16x16x32_bf16 v[70:73], v[150:153], v[214:217], v[70:73]
	v_mfma_f32_16x16x32_bf16 v[66:69], v[158:161], v[214:217], v[66:69]
	s_setprio 0
	s_waitcnt vmcnt(8)
	s_barrier
	s_add_u32 vcc_lo, s44, 0xfff80080
	s_addc_u32 vcc_hi, s45, -1
	s_mov_b32 m0, s70
	s_nop 0
	global_load_lds_dwordx4 v190, vcc
	ds_read_b128 v[162:165], v222 offset:49152
	ds_read_b128 v[166:169], v222 offset:50176
	s_mov_b32 m0, s71
	s_add_i32 s44, s77, s53
	global_load_lds_dwordx4 v206, vcc
	ds_read_b128 v[170:173], v222 offset:51200
	ds_read_b128 v[174:177], v222 offset:52224
	s_add_u32 vcc_lo, s42, 0x80
	s_addc_u32 vcc_hi, s43, 0
	s_mov_b32 m0, s44
	s_nop 0
	global_load_lds_dwordx4 v192, vcc
	ds_read_b128 v[178:181], v222 offset:53248
	ds_read_b128 v[182:185], v222 offset:54272
	s_add_i32 m0, s44, 0x2000
	s_add_u32 s42, s42, 0x80080
	s_addc_u32 s43, s43, 0
	global_load_lds_dwordx4 v208, vcc
	ds_read_b128 v[186:189], v222 offset:55296
	ds_read_b128 v[214:217], v222 offset:56320
	s_add_i32 s44, s79, s53
	s_mov_b32 m0, s44
	s_nop 0
	global_load_lds_dwordx4 v192, s[42:43]
	s_add_i32 m0, s44, 0x2000
	s_nop 0
	global_load_lds_dwordx4 v208, s[42:43]
	s_cmp_lg_u32 s10, 0
	s_cbranch_scc1 .Lh0w_g2_4
	s_waitcnt vmcnt(8)
.Lh0w_g2_4:
	s_waitcnt lgkmcnt(0)
	s_barrier
	s_setprio 1
	s_waitcnt lgkmcnt(0)
	v_mfma_f32_16x16x32_bf16 v[62:65], v[118:121], v[162:165], v[62:65]
	v_mfma_f32_16x16x32_bf16 v[58:61], v[130:133], v[162:165], v[58:61]
	v_mfma_f32_16x16x32_bf16 v[46:49], v[118:121], v[170:173], v[46:49]
	v_mfma_f32_16x16x32_bf16 v[42:45], v[130:133], v[170:173], v[42:45]
	v_mfma_f32_16x16x32_bf16 v[30:33], v[118:121], v[178:181], v[30:33]
	v_mfma_f32_16x16x32_bf16 v[26:29], v[130:133], v[178:181], v[26:29]
	v_mfma_f32_16x16x32_bf16 v[14:17], v[118:121], v[186:189], v[14:17]
	v_mfma_f32_16x16x32_bf16 v[10:13], v[130:133], v[186:189], v[10:13]
	v_mfma_f32_16x16x32_bf16 v[62:65], v[122:125], v[166:169], v[62:65]
	v_mfma_f32_16x16x32_bf16 v[58:61], v[134:137], v[166:169], v[58:61]
	v_mfma_f32_16x16x32_bf16 v[46:49], v[122:125], v[174:177], v[46:49]
	v_mfma_f32_16x16x32_bf16 v[42:45], v[134:137], v[174:177], v[42:45]
	v_mfma_f32_16x16x32_bf16 v[30:33], v[122:125], v[182:185], v[30:33]
	v_mfma_f32_16x16x32_bf16 v[26:29], v[134:137], v[182:185], v[26:29]
	v_mfma_f32_16x16x32_bf16 v[14:17], v[122:125], v[214:217], v[14:17]
	v_mfma_f32_16x16x32_bf16 v[10:13], v[134:137], v[214:217], v[10:13]
	s_setprio 0
	s_setprio 1
	v_mfma_f32_16x16x32_bf16 v[54:57], v[146:149], v[162:165], v[54:57]
	v_mfma_f32_16x16x32_bf16 v[50:53], v[154:157], v[162:165], v[50:53]
	v_mfma_f32_16x16x32_bf16 v[38:41], v[146:149], v[170:173], v[38:41]
	v_mfma_f32_16x16x32_bf16 v[34:37], v[154:157], v[170:173], v[34:37]
	v_mfma_f32_16x16x32_bf16 v[22:25], v[146:149], v[178:181], v[22:25]
	v_mfma_f32_16x16x32_bf16 v[18:21], v[154:157], v[178:181], v[18:21]
	v_mfma_f32_16x16x32_bf16 v[6:9], v[146:149], v[186:189], v[6:9]
	v_mfma_f32_16x16x32_bf16 v[2:5], v[154:157], v[186:189], v[2:5]
	v_mfma_f32_16x16x32_bf16 v[54:57], v[150:153], v[166:169], v[54:57]
	v_mfma_f32_16x16x32_bf16 v[50:53], v[158:161], v[166:169], v[50:53]
	v_mfma_f32_16x16x32_bf16 v[38:41], v[150:153], v[174:177], v[38:41]
	v_mfma_f32_16x16x32_bf16 v[34:37], v[158:161], v[174:177], v[34:37]
	v_mfma_f32_16x16x32_bf16 v[22:25], v[150:153], v[182:185], v[22:25]
	v_mfma_f32_16x16x32_bf16 v[18:21], v[158:161], v[182:185], v[18:21]
	v_mfma_f32_16x16x32_bf16 v[6:9], v[150:153], v[214:217], v[6:9]
	v_mfma_f32_16x16x32_bf16 v[2:5], v[158:161], v[214:217], v[2:5]
	s_setprio 0
	s_waitcnt vmcnt(8)
	s_barrier
	s_add_i32 s76, s76, 2
	s_add_u32 s40, s40, 0x100
	s_addc_u32 s41, s41, 0
	s_add_u32 s74, s74, 0x100
	s_addc_u32 s75, s75, 0
	s_cmp_gt_u32 s76, 29
	s_cbranch_scc0 .LBB0_524
	s_and_b64 vcc, exec, s[10:11]
	s_cbranch_vccz .LBB0_527
	s_barrier

; #define PG8_STAGE(bufoff, gbase, voff) do { _Pragma("unroll") for (int _i = 0; _i < 2; ++_i) \
;         __builtin_amdgcn_global_load_lds((const unsigned*)((const char*)(gbase) + (voff)[_i]), (PG8_LAS unsigned*)(lds + (bufoff) + ldsw + _i * 8192), 16, 0, 0); } while (0)
; #define PG8_LDA(dst, b, h) do { _Pragma("unroll") for (int m = 0; m < 4; ++m) _Pragma("unroll") for (int k = 0; k < 2; ++k) dst[m][k] = *(const PG8_LAS bf16x8*)(lds + PG8_SA(b, h) + aoff + m * 2048 + k * 1024); } while (0)
; #define PG8_LDB(dst, b, h) do { _Pragma("unroll") for (int n = 0; n < 2; ++n) _Pragma("unroll") for (int k = 0; k < 2; ++k) dst[n][k] = *(const PG8_LAS bf16x8*)(lds + PG8_SB(b, h) + boff + n * 2048 + k * 1024); } while (0)
; #define PG8_MMA(ai, bj, At, Bt) do { __builtin_amdgcn_s_setprio(1); _Pragma("unroll") for (int m = 0; m < 4; ++m) _Pragma("unroll") for (int n = 0; n < 2; ++n) _Pragma("unroll") for (int k = 0; k < 2; ++k) \
;         acc[ai][bj][m][n] = __builtin_amdgcn_mfma_f32_16x16x32_bf16(Bt[n][k], At[m][k], acc[ai][bj][m][n], 0, 0, 0); __builtin_amdgcn_s_setprio(0); } while (0)
; #define PG8_WAIT_V(n) asm volatile("s_waitcnt vmcnt(" #n ")" ::: "memory")
; #define PG8_WAIT_L(n) asm volatile("s_waitcnt lgkmcnt(" #n ")" ::: "memory")
; #define PG8_BAR __builtin_amdgcn_s_barrier()
; #define PG8_SCHED __builtin_amdgcn_sched_barrier(0)
; template <class Epi, class Sched, bool ALIGN_EPI = false, bool SP2 = false>
; __device__ __forceinline__ void gemm_phase(PG8_LAS unsigned char* lds, const Gemm g, const Sched& S, const Epi& E, const int wave_id) {
;     ...
;             PG8_LDB(B0, 0, 0); PG8_LDB(B1, 0, 1); PG8_SCHED; PG8_LDA(At, 0, 0); PG8_STAGE(PG8_SA(1, 1), a1 + hstep, voffA);
;             PG8_WAIT_V(8); PG8_WAIT_L(0); PG8_BAR; PG8_MMA(0, 0, At, B0); PG8_MMA(0, 1, At, B1); PG8_BAR; PG8_SCHED;
;             PG8_LDA(At, 0, 1); PG8_STAGE(PG8_SB(0, 0), b2, voffB); PG8_STAGE(PG8_SB(0, 1), b2 + hstep, voffB); PG8_STAGE(PG8_SA(0, 0), a2, voffA);
;             PG8_WAIT_V(8); PG8_WAIT_L(0); PG8_BAR; PG8_MMA(1, 0, At, B0); PG8_MMA(1, 1, At, B1); PG8_BAR; PG8_SCHED;
.LBB0_641:
	s_add_u32 s42, s20, 0xfff80080
	s_addc_u32 s43, s21, -1
	s_add_i32 s76, 0, 0x10000
	s_cmp_eq_u32 s75, 28
	s_cselect_b32 s45, s15, s43
	s_cselect_b32 s44, s71, s42
	s_cselect_b32 s43, s13, s74
	s_cselect_b32 s42, s72, s73
	s_add_i32 s79, 0, 0x14000
	s_add_i32 m0, s53, 0xc000
	s_nop 0
	global_load_lds_dwordx4 v138, s[20:21]
	ds_read_b128 v[158:161], v144
	ds_read_b128 v[162:165], v144 offset:1024
	ds_read_b128 v[166:169], v144 offset:2048
	ds_read_b128 v[170:173], v144 offset:3072
	ds_read_b128 v[174:177], v144 offset:16384
	ds_read_b128 v[178:181], v144 offset:17408
	ds_read_b128 v[182:185], v144 offset:18432
	ds_read_b128 v[186:189], v144 offset:19456
	s_add_i32 m0, s53, 0xe000
	s_nop 0
	global_load_lds_dwordx4 v140, s[20:21]
	ds_read_b128 v[190:193], v155
	ds_read_b128 v[206:209], v155 offset:1024
	ds_read_b128 v[210:213], v155 offset:2048
	ds_read_b128 v[214:217], v155 offset:3072
	ds_read_b128 v[226:229], v155 offset:4096
	ds_read_b128 v[234:237], v155 offset:5120
	ds_read_b128 v[238:241], v155 offset:6144
	ds_read_b128 v[242:245], v155 offset:7168
	s_cmp_lg_u32 s10, 0
	s_cbranch_scc1 .Lh0w_g3_1
	s_waitcnt vmcnt(8)
.Lh0w_g3_1:
	s_waitcnt lgkmcnt(0)
	s_barrier
	s_setprio 1
	s_waitcnt lgkmcnt(0)
	v_mfma_f32_16x16x32_bf16 v[126:129], v[158:161], v[190:193], v[126:129]
	v_mfma_f32_16x16x32_bf16 v[118:121], v[166:169], v[190:193], v[118:121]
	v_mfma_f32_16x16x32_bf16 v[110:113], v[158:161], v[210:213], v[110:113]
	v_mfma_f32_16x16x32_bf16 v[102:105], v[166:169], v[210:213], v[102:105]
	v_mfma_f32_16x16x32_bf16 v[94:97], v[158:161], v[226:229], v[94:97]
	v_mfma_f32_16x16x32_bf16 v[86:89], v[166:169], v[226:229], v[86:89]
	v_mfma_f32_16x16x32_bf16 v[78:81], v[158:161], v[238:241], v[78:81]
	v_mfma_f32_16x16x32_bf16 v[70:73], v[166:169], v[238:241], v[70:73]
	v_mfma_f32_16x16x32_bf16 v[126:129], v[162:165], v[206:209], v[126:129]
	v_mfma_f32_16x16x32_bf16 v[118:121], v[170:173], v[206:209], v[118:121]
	v_mfma_f32_16x16x32_bf16 v[110:113], v[162:165], v[214:217], v[110:113]
	v_mfma_f32_16x16x32_bf16 v[102:105], v[170:173], v[214:217], v[102:105]
	v_mfma_f32_16x16x32_bf16 v[94:97], v[162:165], v[234:237], v[94:97]
	v_mfma_f32_16x16x32_bf16 v[86:89], v[170:173], v[234:237], v[86:89]
	v_mfma_f32_16x16x32_bf16 v[78:81], v[162:165], v[242:245], v[78:81]
	v_mfma_f32_16x16x32_bf16 v[70:73], v[170:173], v[242:245], v[70:73]
	s_setprio 0
	s_setprio 1
	v_mfma_f32_16x16x32_bf16 v[122:125], v[174:177], v[190:193], v[122:125]
	v_mfma_f32_16x16x32_bf16 v[114:117], v[182:185], v[190:193], v[114:117]
	v_mfma_f32_16x16x32_bf16 v[106:109], v[174:177], v[210:213], v[106:109]
	v_mfma_f32_16x16x32_bf16 v[98:101], v[182:185], v[210:213], v[98:101]
	v_mfma_f32_16x16x32_bf16 v[90:93], v[174:177], v[226:229], v[90:93]
	v_mfma_f32_16x16x32_bf16 v[82:85], v[182:185], v[226:229], v[82:85]
	v_mfma_f32_16x16x32_bf16 v[74:77], v[174:177], v[238:241], v[74:77]
	v_mfma_f32_16x16x32_bf16 v[66:69], v[182:185], v[238:241], v[66:69]
	v_mfma_f32_16x16x32_bf16 v[122:125], v[178:181], v[206:209], v[122:125]
	v_mfma_f32_16x16x32_bf16 v[114:117], v[186:189], v[206:209], v[114:117]
	v_mfma_f32_16x16x32_bf16 v[106:109], v[178:181], v[214:217], v[106:109]
	v_mfma_f32_16x16x32_bf16 v[98:101], v[186:189], v[214:217], v[98:101]
	v_mfma_f32_16x16x32_bf16 v[90:93], v[178:181], v[234:237], v[90:93]
	v_mfma_f32_16x16x32_bf16 v[82:85], v[186:189], v[234:237], v[82:85]
	v_mfma_f32_16x16x32_bf16 v[74:77], v[178:181], v[242:245], v[74:77]
	v_mfma_f32_16x16x32_bf16 v[66:69], v[186:189], v[242:245], v[66:69]
	s_setprio 0
	s_waitcnt vmcnt(8)
	s_barrier
	s_add_i32 s76, s76, s41
	s_mov_b32 m0, s76
	s_nop 0
	global_load_lds_dwordx4 v132, s[42:43]
	ds_read_b128 v[190:193], v155 offset:16384
	ds_read_b128 v[206:209], v155 offset:17408
	s_add_i32 m0, s76, 0x2000
	s_add_u32 s76, s42, 0x80000
	s_addc_u32 s77, s43, 0
	s_add_i32 s79, s79, s41
	global_load_lds_dwordx4 v136, s[42:43]
	ds_read_b128 v[210:213], v155 offset:18432
	ds_read_b128 v[214:217], v155 offset:19456
	s_mov_b32 m0, s79
	s_nop 0
	global_load_lds_dwordx4 v132, s[76:77]
	ds_read_b128 v[226:229], v155 offset:20480
	ds_read_b128 v[234:237], v155 offset:21504
	s_add_i32 m0, s79, 0x2000
	s_nop 0
	global_load_lds_dwordx4 v136, s[76:77]
	ds_read_b128 v[238:241], v155 offset:22528
	ds_read_b128 v[242:245], v155 offset:23552
	s_mov_b32 m0, s53
	s_nop 0
	global_load_lds_dwordx4 v130, s[44:45]
	s_mov_b32 m0, s56
	s_nop 0
	global_load_lds_dwordx4 v134, s[44:45]
	s_cmp_lg_u32 s10, 0
	s_cbranch_scc1 .Lh0w_g3_2
	s_waitcnt vmcnt(8)
; #define PG8_STAGE(bufoff, gbase, voff) do { _Pragma("unroll") for (int _i = 0; _i < 2; ++_i) \
;         __builtin_amdgcn_global_load_lds((const unsigned*)((const char*)(gbase) + (voff)[_i]), (PG8_LAS unsigned*)(lds + (bufoff) + ldsw + _i * 8192), 16, 0, 0); } while (0)
; #define PG8_LDA(dst, b, h) do { _Pragma("unroll") for (int m = 0; m < 4; ++m) _Pragma("unroll") for (int k = 0; k < 2; ++k) dst[m][k] = *(const PG8_LAS bf16x8*)(lds + PG8_SA(b, h) + aoff + m * 2048 + k * 1024); } while (0)
; #define PG8_LDB(dst, b, h) do { _Pragma("unroll") for (int n = 0; n < 2; ++n) _Pragma("unroll") for (int k = 0; k < 2; ++k) dst[n][k] = *(const PG8_LAS bf16x8*)(lds + PG8_SB(b, h) + boff + n * 2048 + k * 1024); } while (0)
; #define PG8_MMA(ai, bj, At, Bt) do { __builtin_amdgcn_s_setprio(1); _Pragma("unroll") for (int m = 0; m < 4; ++m) _Pragma("unroll") for (int n = 0; n < 2; ++n) _Pragma("unroll") for (int k = 0; k < 2; ++k) \
;         acc[ai][bj][m][n] = __builtin_amdgcn_mfma_f32_16x16x32_bf16(Bt[n][k], At[m][k], acc[ai][bj][m][n], 0, 0, 0); __builtin_amdgcn_s_setprio(0); } while (0)
; #define PG8_WAIT_V(n) asm volatile("s_waitcnt vmcnt(" #n ")" ::: "memory")
; #define PG8_WAIT_L(n) asm volatile("s_waitcnt lgkmcnt(" #n ")" ::: "memory")
; #define PG8_BAR __builtin_amdgcn_s_barrier()
; #define PG8_SCHED __builtin_amdgcn_sched_barrier(0)
; template <class Epi, class Sched, bool ALIGN_EPI = false, bool SP2 = false>
; __device__ __forceinline__ void gemm_phase(PG8_LAS unsigned char* lds, const Gemm g, const Sched& S, const Epi& E, const int wave_id) {
;     ...
;             PG8_WAIT_V(8); PG8_WAIT_L(0); PG8_BAR; PG8_MMA(1, 0, At, B0); PG8_MMA(1, 1, At, B1); PG8_BAR; PG8_SCHED;
;             PG8_LDB(B0, 1, 0); PG8_LDB(B1, 1, 1); PG8_SCHED; PG8_LDA(At, 1, 0); PG8_STAGE(PG8_SA(0, 1), a2 + hstep, voffA);
.Lh0w_g3_2:
	s_waitcnt lgkmcnt(0)
	s_barrier
	s_setprio 1
	s_waitcnt lgkmcnt(0)
	v_mfma_f32_16x16x32_bf16 v[62:65], v[158:161], v[190:193], v[62:65]
	v_mfma_f32_16x16x32_bf16 v[54:57], v[166:169], v[190:193], v[54:57]
	v_mfma_f32_16x16x32_bf16 v[46:49], v[158:161], v[210:213], v[46:49]
	v_mfma_f32_16x16x32_bf16 v[38:41], v[166:169], v[210:213], v[38:41]
	v_mfma_f32_16x16x32_bf16 v[30:33], v[158:161], v[226:229], v[30:33]
	v_mfma_f32_16x16x32_bf16 v[22:25], v[166:169], v[226:229], v[22:25]
	v_mfma_f32_16x16x32_bf16 v[14:17], v[158:161], v[238:241], v[14:17]
	v_mfma_f32_16x16x32_bf16 v[6:9], v[166:169], v[238:241], v[6:9]
	v_mfma_f32_16x16x32_bf16 v[62:65], v[162:165], v[206:209], v[62:65]
	v_mfma_f32_16x16x32_bf16 v[54:57], v[170:173], v[206:209], v[54:57]
	v_mfma_f32_16x16x32_bf16 v[46:49], v[162:165], v[214:217], v[46:49]
	v_mfma_f32_16x16x32_bf16 v[38:41], v[170:173], v[214:217], v[38:41]
	v_mfma_f32_16x16x32_bf16 v[30:33], v[162:165], v[234:237], v[30:33]
	v_mfma_f32_16x16x32_bf16 v[22:25], v[170:173], v[234:237], v[22:25]
	v_mfma_f32_16x16x32_bf16 v[14:17], v[162:165], v[242:245], v[14:17]
	v_mfma_f32_16x16x32_bf16 v[6:9], v[170:173], v[242:245], v[6:9]
	s_setprio 0
	s_setprio 1
	v_mfma_f32_16x16x32_bf16 v[58:61], v[174:177], v[190:193], v[58:61]
	v_mfma_f32_16x16x32_bf16 v[50:53], v[182:185], v[190:193], v[50:53]
	v_mfma_f32_16x16x32_bf16 v[42:45], v[174:177], v[210:213], v[42:45]
	v_mfma_f32_16x16x32_bf16 v[34:37], v[182:185], v[210:213], v[34:37]
	v_mfma_f32_16x16x32_bf16 v[26:29], v[174:177], v[226:229], v[26:29]
	v_mfma_f32_16x16x32_bf16 v[18:21], v[182:185], v[226:229], v[18:21]
	v_mfma_f32_16x16x32_bf16 v[10:13], v[174:177], v[238:241], v[10:13]
	v_mfma_f32_16x16x32_bf16 v[2:5], v[182:185], v[238:241], v[2:5]
	v_mfma_f32_16x16x32_bf16 v[58:61], v[178:181], v[206:209], v[58:61]
	v_mfma_f32_16x16x32_bf16 v[50:53], v[186:189], v[206:209], v[50:53]
	v_mfma_f32_16x16x32_bf16 v[42:45], v[178:181], v[214:217], v[42:45]
	v_mfma_f32_16x16x32_bf16 v[34:37], v[186:189], v[214:217], v[34:37]
	v_mfma_f32_16x16x32_bf16 v[26:29], v[178:181], v[234:237], v[26:29]
	v_mfma_f32_16x16x32_bf16 v[18:21], v[186:189], v[234:237], v[18:21]
	v_mfma_f32_16x16x32_bf16 v[10:13], v[178:181], v[242:245], v[10:13]
	v_mfma_f32_16x16x32_bf16 v[2:5], v[186:189], v[242:245], v[2:5]
	s_setprio 0
	s_waitcnt vmcnt(8)
	s_barrier
	s_add_i32 s76, 0, 0x18000
	s_add_i32 s77, 0, 0x1c000
	s_add_u32 s44, s44, 0x80000
	s_addc_u32 s45, s45, 0
	s_mov_b32 m0, s57
	s_nop 0
	global_load_lds_dwordx4 v130, s[44:45]
	ds_read_b128 v[158:161], v144 offset:32768
	ds_read_b128 v[162:165], v144 offset:33792
	ds_read_b128 v[166:169], v144 offset:34816
	ds_read_b128 v[170:173], v144 offset:35840
	ds_read_b128 v[174:177], v144 offset:49152
	ds_read_b128 v[178:181], v144 offset:50176
	ds_read_b128 v[182:185], v144 offset:51200
	ds_read_b128 v[186:189], v144 offset:52224
	s_mov_b32 m0, s64
	s_nop 0
	global_load_lds_dwordx4 v134, s[44:45]
	ds_read_b128 v[190:193], v155 offset:32768
	ds_read_b128 v[206:209], v155 offset:33792
	ds_read_b128 v[210:213], v155 offset:34816
	ds_read_b128 v[214:217], v155 offset:35840
	ds_read_b128 v[226:229], v155 offset:36864
	ds_read_b128 v[234:237], v155 offset:37888
	ds_read_b128 v[238:241], v155 offset:38912
	ds_read_b128 v[242:245], v155 offset:39936
	s_cmp_lg_u32 s10, 0
	s_cbranch_scc1 .Lh0w_g3_3
	s_waitcnt vmcnt(8)
; #define PG8_STAGE(bufoff, gbase, voff) do { _Pragma("unroll") for (int _i = 0; _i < 2; ++_i) \
;         __builtin_amdgcn_global_load_lds((const unsigned*)((const char*)(gbase) + (voff)[_i]), (PG8_LAS unsigned*)(lds + (bufoff) + ldsw + _i * 8192), 16, 0, 0); } while (0)
; #define PG8_LDA(dst, b, h) do { _Pragma("unroll") for (int m = 0; m < 4; ++m) _Pragma("unroll") for (int k = 0; k < 2; ++k) dst[m][k] = *(const PG8_LAS bf16x8*)(lds + PG8_SA(b, h) + aoff + m * 2048 + k * 1024); } while (0)
; #define PG8_MMA(ai, bj, At, Bt) do { __builtin_amdgcn_s_setprio(1); _Pragma("unroll") for (int m = 0; m < 4; ++m) _Pragma("unroll") for (int n = 0; n < 2; ++n) _Pragma("unroll") for (int k = 0; k < 2; ++k) \
;         acc[ai][bj][m][n] = __builtin_amdgcn_mfma_f32_16x16x32_bf16(Bt[n][k], At[m][k], acc[ai][bj][m][n], 0, 0, 0); __builtin_amdgcn_s_setprio(0); } while (0)
; #define PG8_WAIT_V(n) asm volatile("s_waitcnt vmcnt(" #n ")" ::: "memory")
; #define PG8_WAIT_L(n) asm volatile("s_waitcnt lgkmcnt(" #n ")" ::: "memory")
; #define PG8_BAR __builtin_amdgcn_s_barrier()
; #define PG8_SCHED __builtin_amdgcn_sched_barrier(0)
; template <class Epi, class Sched, bool ALIGN_EPI = false, bool SP2 = false>
; __device__ __forceinline__ void gemm_phase(PG8_LAS unsigned char* lds, const Gemm g, const Sched& S, const Epi& E, const int wave_id) {
;     ...
;             PG8_WAIT_V(8); PG8_WAIT_L(0); PG8_BAR; PG8_MMA(0, 0, At, B0); PG8_MMA(0, 1, At, B1); PG8_BAR; PG8_SCHED;
;             PG8_LDA(At, 1, 1); PG8_STAGE(PG8_SB(1, 0), b3, voffB); PG8_STAGE(PG8_SB(1, 1), b3 + hstep, voffB); PG8_STAGE(PG8_SA(1, 0), a3, voffA);
;             PG8_WAIT_V(8); PG8_WAIT_L(0); PG8_BAR; PG8_MMA(1, 0, At, B0); PG8_MMA(1, 1, At, B1); PG8_BAR; PG8_SCHED;
.Lh0w_g3_3:
	s_waitcnt lgkmcnt(0)
	s_barrier
	s_setprio 1
	s_waitcnt lgkmcnt(0)
	v_mfma_f32_16x16x32_bf16 v[126:129], v[158:161], v[190:193], v[126:129]
	v_mfma_f32_16x16x32_bf16 v[118:121], v[166:169], v[190:193], v[118:121]
	v_mfma_f32_16x16x32_bf16 v[110:113], v[158:161], v[210:213], v[110:113]
	v_mfma_f32_16x16x32_bf16 v[102:105], v[166:169], v[210:213], v[102:105]
	v_mfma_f32_16x16x32_bf16 v[94:97], v[158:161], v[226:229], v[94:97]
	v_mfma_f32_16x16x32_bf16 v[86:89], v[166:169], v[226:229], v[86:89]
	v_mfma_f32_16x16x32_bf16 v[78:81], v[158:161], v[238:241], v[78:81]
	v_mfma_f32_16x16x32_bf16 v[70:73], v[166:169], v[238:241], v[70:73]
	v_mfma_f32_16x16x32_bf16 v[126:129], v[162:165], v[206:209], v[126:129]
	v_mfma_f32_16x16x32_bf16 v[118:121], v[170:173], v[206:209], v[118:121]
	v_mfma_f32_16x16x32_bf16 v[110:113], v[162:165], v[214:217], v[110:113]
	v_mfma_f32_16x16x32_bf16 v[102:105], v[170:173], v[214:217], v[102:105]
	v_mfma_f32_16x16x32_bf16 v[94:97], v[162:165], v[234:237], v[94:97]
	v_mfma_f32_16x16x32_bf16 v[86:89], v[170:173], v[234:237], v[86:89]
	v_mfma_f32_16x16x32_bf16 v[78:81], v[162:165], v[242:245], v[78:81]
	v_mfma_f32_16x16x32_bf16 v[70:73], v[170:173], v[242:245], v[70:73]
	s_setprio 0
	s_setprio 1
	v_mfma_f32_16x16x32_bf16 v[122:125], v[174:177], v[190:193], v[122:125]
	v_mfma_f32_16x16x32_bf16 v[114:117], v[182:185], v[190:193], v[114:117]
	v_mfma_f32_16x16x32_bf16 v[106:109], v[174:177], v[210:213], v[106:109]
	v_mfma_f32_16x16x32_bf16 v[98:101], v[182:185], v[210:213], v[98:101]
	v_mfma_f32_16x16x32_bf16 v[90:93], v[174:177], v[226:229], v[90:93]
	v_mfma_f32_16x16x32_bf16 v[82:85], v[182:185], v[226:229], v[82:85]
	v_mfma_f32_16x16x32_bf16 v[74:77], v[174:177], v[238:241], v[74:77]
	v_mfma_f32_16x16x32_bf16 v[66:69], v[182:185], v[238:241], v[66:69]
	v_mfma_f32_16x16x32_bf16 v[122:125], v[178:181], v[206:209], v[122:125]
	v_mfma_f32_16x16x32_bf16 v[114:117], v[186:189], v[206:209], v[114:117]
	v_mfma_f32_16x16x32_bf16 v[106:109], v[178:181], v[214:217], v[106:109]
	v_mfma_f32_16x16x32_bf16 v[98:101], v[186:189], v[214:217], v[98:101]
	v_mfma_f32_16x16x32_bf16 v[90:93], v[178:181], v[234:237], v[90:93]
	v_mfma_f32_16x16x32_bf16 v[82:85], v[186:189], v[234:237], v[82:85]
	v_mfma_f32_16x16x32_bf16 v[74:77], v[178:181], v[242:245], v[74:77]
	v_mfma_f32_16x16x32_bf16 v[66:69], v[186:189], v[242:245], v[66:69]
	s_setprio 0
	s_waitcnt vmcnt(8)
	s_barrier
	s_add_u32 vcc_lo, s44, 0xfff80080
	s_addc_u32 vcc_hi, s45, -1
	s_mov_b32 m0, s65
	s_nop 0
	global_load_lds_dwordx4 v130, vcc
	ds_read_b128 v[190:193], v155 offset:49152
	ds_read_b128 v[206:209], v155 offset:50176
	s_mov_b32 m0, s68
	s_add_i32 s44, s76, s41
	global_load_lds_dwordx4 v134, vcc
	ds_read_b128 v[210:213], v155 offset:51200
	ds_read_b128 v[214:217], v155 offset:52224
	s_add_u32 vcc_lo, s42, 0x80
	s_addc_u32 vcc_hi, s43, 0
	s_mov_b32 m0, s44
	s_nop 0
	global_load_lds_dwordx4 v132, vcc
	ds_read_b128 v[226:229], v155 offset:53248
	ds_read_b128 v[234:237], v155 offset:54272
	s_add_i32 m0, s44, 0x2000
	s_add_u32 s42, s42, 0x80080
	s_addc_u32 s43, s43, 0
	global_load_lds_dwordx4 v136, vcc
	ds_read_b128 v[238:241], v155 offset:55296
	ds_read_b128 v[242:245], v155 offset:56320
	s_add_i32 s44, s77, s41
	s_mov_b32 m0, s44
	s_nop 0
	global_load_lds_dwordx4 v132, s[42:43]
	s_add_i32 m0, s44, 0x2000
	s_nop 0
	global_load_lds_dwordx4 v136, s[42:43]
	s_cmp_lg_u32 s10, 0
	s_cbranch_scc1 .Lh0w_g3_4
	s_waitcnt vmcnt(8)
.Lh0w_g3_4:
	s_waitcnt lgkmcnt(0)
	s_barrier
	s_setprio 1
	s_waitcnt lgkmcnt(0)
	v_mfma_f32_16x16x32_bf16 v[62:65], v[158:161], v[190:193], v[62:65]
	v_mfma_f32_16x16x32_bf16 v[54:57], v[166:169], v[190:193], v[54:57]
	v_mfma_f32_16x16x32_bf16 v[46:49], v[158:161], v[210:213], v[46:49]
	v_mfma_f32_16x16x32_bf16 v[38:41], v[166:169], v[210:213], v[38:41]
	v_mfma_f32_16x16x32_bf16 v[30:33], v[158:161], v[226:229], v[30:33]
	v_mfma_f32_16x16x32_bf16 v[22:25], v[166:169], v[226:229], v[22:25]
	v_mfma_f32_16x16x32_bf16 v[14:17], v[158:161], v[238:241], v[14:17]
	v_mfma_f32_16x16x32_bf16 v[6:9], v[166:169], v[238:241], v[6:9]
	v_mfma_f32_16x16x32_bf16 v[62:65], v[162:165], v[206:209], v[62:65]
	v_mfma_f32_16x16x32_bf16 v[54:57], v[170:173], v[206:209], v[54:57]
	v_mfma_f32_16x16x32_bf16 v[46:49], v[162:165], v[214:217], v[46:49]
	v_mfma_f32_16x16x32_bf16 v[38:41], v[170:173], v[214:217], v[38:41]
	v_mfma_f32_16x16x32_bf16 v[30:33], v[162:165], v[234:237], v[30:33]
	v_mfma_f32_16x16x32_bf16 v[22:25], v[170:173], v[234:237], v[22:25]
	v_mfma_f32_16x16x32_bf16 v[14:17], v[162:165], v[242:245], v[14:17]
	v_mfma_f32_16x16x32_bf16 v[6:9], v[170:173], v[242:245], v[6:9]
	s_setprio 0
	s_setprio 1
	v_mfma_f32_16x16x32_bf16 v[58:61], v[174:177], v[190:193], v[58:61]
	v_mfma_f32_16x16x32_bf16 v[50:53], v[182:185], v[190:193], v[50:53]
	v_mfma_f32_16x16x32_bf16 v[42:45], v[174:177], v[210:213], v[42:45]
	v_mfma_f32_16x16x32_bf16 v[34:37], v[182:185], v[210:213], v[34:37]
	v_mfma_f32_16x16x32_bf16 v[26:29], v[174:177], v[226:229], v[26:29]
	v_mfma_f32_16x16x32_bf16 v[18:21], v[182:185], v[226:229], v[18:21]
	v_mfma_f32_16x16x32_bf16 v[10:13], v[174:177], v[238:241], v[10:13]
	v_mfma_f32_16x16x32_bf16 v[2:5], v[182:185], v[238:241], v[2:5]
	v_mfma_f32_16x16x32_bf16 v[58:61], v[178:181], v[206:209], v[58:61]
	v_mfma_f32_16x16x32_bf16 v[50:53], v[186:189], v[206:209], v[50:53]
	v_mfma_f32_16x16x32_bf16 v[42:45], v[178:181], v[214:217], v[42:45]
	v_mfma_f32_16x16x32_bf16 v[34:37], v[186:189], v[214:217], v[34:37]
	v_mfma_f32_16x16x32_bf16 v[26:29], v[178:181], v[234:237], v[26:29]
	v_mfma_f32_16x16x32_bf16 v[18:21], v[186:189], v[234:237], v[18:21]
	v_mfma_f32_16x16x32_bf16 v[10:13], v[178:181], v[242:245], v[10:13]
	v_mfma_f32_16x16x32_bf16 v[2:5], v[186:189], v[242:245], v[2:5]
	s_setprio 0
	s_waitcnt vmcnt(8)
	s_barrier
	s_add_i32 s75, s75, 2
	s_add_u32 s20, s20, 0x100
	s_addc_u32 s21, s21, 0
	s_add_u32 s73, s73, 0x100
	s_addc_u32 s74, s74, 0
	s_cmp_gt_u32 s75, 29
	s_cbranch_scc0 .LBB0_641
	s_and_b64 vcc, exec, s[10:11]
	s_cbranch_vccz .LBB0_644
	s_barrier

; #define PG8_STAGE(bufoff, gbase, voff) do { _Pragma("unroll") for (int _i = 0; _i < 2; ++_i) \
;         __builtin_amdgcn_global_load_lds((const unsigned*)((const char*)(gbase) + (voff)[_i]), (PG8_LAS unsigned*)(lds + (bufoff) + ldsw + _i * 8192), 16, 0, 0); } while (0)
; #define PG8_LDA(dst, b, h) do { _Pragma("unroll") for (int m = 0; m < 4; ++m) _Pragma("unroll") for (int k = 0; k < 2; ++k) dst[m][k] = *(const PG8_LAS bf16x8*)(lds + PG8_SA(b, h) + aoff + m * 2048 + k * 1024); } while (0)
; #define PG8_LDB(dst, b, h) do { _Pragma("unroll") for (int n = 0; n < 2; ++n) _Pragma("unroll") for (int k = 0; k < 2; ++k) dst[n][k] = *(const PG8_LAS bf16x8*)(lds + PG8_SB(b, h) + boff + n * 2048 + k * 1024); } while (0)
; #define PG8_MMA(ai, bj, At, Bt) do { __builtin_amdgcn_s_setprio(1); _Pragma("unroll") for (int m = 0; m < 4; ++m) _Pragma("unroll") for (int n = 0; n < 2; ++n) _Pragma("unroll") for (int k = 0; k < 2; ++k) \
;         acc[ai][bj][m][n] = __builtin_amdgcn_mfma_f32_16x16x32_bf16(Bt[n][k], At[m][k], acc[ai][bj][m][n], 0, 0, 0); __builtin_amdgcn_s_setprio(0); } while (0)
; #define PG8_WAIT_V(n) asm volatile("s_waitcnt vmcnt(" #n ")" ::: "memory")
; #define PG8_WAIT_L(n) asm volatile("s_waitcnt lgkmcnt(" #n ")" ::: "memory")
; #define PG8_BAR __builtin_amdgcn_s_barrier()
; #define PG8_SCHED __builtin_amdgcn_sched_barrier(0)
; template <class Epi, class Sched, bool ALIGN_EPI = false, bool SP2 = false>
; __device__ __forceinline__ void gemm_phase(PG8_LAS unsigned char* lds, const Gemm g, const Sched& S, const Epi& E, const int wave_id) {
;     ...
;             PG8_LDB(B0, 0, 0); PG8_LDB(B1, 0, 1); PG8_SCHED; PG8_LDA(At, 0, 0); PG8_STAGE(PG8_SA(1, 1), a1 + hstep, voffA);
;             PG8_WAIT_V(8); PG8_WAIT_L(0); PG8_BAR; PG8_MMA(0, 0, At, B0); PG8_MMA(0, 1, At, B1); PG8_BAR; PG8_SCHED;
;             PG8_LDA(At, 0, 1); PG8_STAGE(PG8_SB(0, 0), b2, voffB); PG8_STAGE(PG8_SB(0, 1), b2 + hstep, voffB); PG8_STAGE(PG8_SA(0, 0), a2, voffA);
;             PG8_WAIT_V(8); PG8_WAIT_L(0); PG8_BAR; PG8_MMA(1, 0, At, B0); PG8_MMA(1, 1, At, B1); PG8_BAR; PG8_SCHED;
.LBB0_759:
	s_add_u32 s20, s18, 0x100
	s_addc_u32 s21, s19, 0
	s_add_i32 s77, 0, 0x10000
	s_cmpk_eq_i32 s76, 0x54
	s_cselect_b32 s43, s15, s21
	s_cselect_b32 s42, s14, s20
	s_cselect_b32 s41, s17, s75
	s_cselect_b32 s40, s16, s74
	s_add_i32 s79, 0, 0x14000
	s_add_i32 m0, s52, 0xc000
	s_nop 0
	global_load_lds_dwordx4 v210, s[18:19]
	ds_read_b128 v[118:121], v226
	ds_read_b128 v[122:125], v226 offset:1024
	ds_read_b128 v[130:133], v226 offset:2048
	ds_read_b128 v[134:137], v226 offset:3072
	ds_read_b128 v[146:149], v226 offset:16384
	ds_read_b128 v[150:153], v226 offset:17408
	ds_read_b128 v[154:157], v226 offset:18432
	ds_read_b128 v[158:161], v226 offset:19456
	s_add_i32 m0, s52, 0xe000
	s_nop 0
	global_load_lds_dwordx4 v212, s[18:19]
	ds_read_b128 v[162:165], v222
	ds_read_b128 v[166:169], v222 offset:1024
	ds_read_b128 v[170:173], v222 offset:2048
	ds_read_b128 v[174:177], v222 offset:3072
	ds_read_b128 v[178:181], v222 offset:4096
	ds_read_b128 v[182:185], v222 offset:5120
	ds_read_b128 v[186:189], v222 offset:6144
	ds_read_b128 v[214:217], v222 offset:7168
	s_cmp_lg_u32 s10, 0
	s_cbranch_scc1 .Lh0w_g4_1
	s_waitcnt vmcnt(8)
.Lh0w_g4_1:
	s_waitcnt lgkmcnt(0)
	s_barrier
	s_setprio 1
	s_waitcnt lgkmcnt(0)
	v_mfma_f32_16x16x32_bf16 v[142:145], v[118:121], v[162:165], v[142:145]
	v_mfma_f32_16x16x32_bf16 v[138:141], v[130:133], v[162:165], v[138:141]
	v_mfma_f32_16x16x32_bf16 v[110:113], v[118:121], v[170:173], v[110:113]
	v_mfma_f32_16x16x32_bf16 v[106:109], v[130:133], v[170:173], v[106:109]
	v_mfma_f32_16x16x32_bf16 v[94:97], v[118:121], v[178:181], v[94:97]
	v_mfma_f32_16x16x32_bf16 v[90:93], v[130:133], v[178:181], v[90:93]
	v_mfma_f32_16x16x32_bf16 v[78:81], v[118:121], v[186:189], v[78:81]
	v_mfma_f32_16x16x32_bf16 v[74:77], v[130:133], v[186:189], v[74:77]
	v_mfma_f32_16x16x32_bf16 v[142:145], v[122:125], v[166:169], v[142:145]
	v_mfma_f32_16x16x32_bf16 v[138:141], v[134:137], v[166:169], v[138:141]
	v_mfma_f32_16x16x32_bf16 v[110:113], v[122:125], v[174:177], v[110:113]
	v_mfma_f32_16x16x32_bf16 v[106:109], v[134:137], v[174:177], v[106:109]
	v_mfma_f32_16x16x32_bf16 v[94:97], v[122:125], v[182:185], v[94:97]
	v_mfma_f32_16x16x32_bf16 v[90:93], v[134:137], v[182:185], v[90:93]
	v_mfma_f32_16x16x32_bf16 v[78:81], v[122:125], v[214:217], v[78:81]
	v_mfma_f32_16x16x32_bf16 v[74:77], v[134:137], v[214:217], v[74:77]
	s_setprio 0
	s_setprio 1
	v_mfma_f32_16x16x32_bf16 v[126:129], v[146:149], v[162:165], v[126:129]
	v_mfma_f32_16x16x32_bf16 v[114:117], v[154:157], v[162:165], v[114:117]
	v_mfma_f32_16x16x32_bf16 v[102:105], v[146:149], v[170:173], v[102:105]
	v_mfma_f32_16x16x32_bf16 v[98:101], v[154:157], v[170:173], v[98:101]
	v_mfma_f32_16x16x32_bf16 v[86:89], v[146:149], v[178:181], v[86:89]
	v_mfma_f32_16x16x32_bf16 v[82:85], v[154:157], v[178:181], v[82:85]
	v_mfma_f32_16x16x32_bf16 v[70:73], v[146:149], v[186:189], v[70:73]
	v_mfma_f32_16x16x32_bf16 v[66:69], v[154:157], v[186:189], v[66:69]
	v_mfma_f32_16x16x32_bf16 v[126:129], v[150:153], v[166:169], v[126:129]
	v_mfma_f32_16x16x32_bf16 v[114:117], v[158:161], v[166:169], v[114:117]
	v_mfma_f32_16x16x32_bf16 v[102:105], v[150:153], v[174:177], v[102:105]
	v_mfma_f32_16x16x32_bf16 v[98:101], v[158:161], v[174:177], v[98:101]
	v_mfma_f32_16x16x32_bf16 v[86:89], v[150:153], v[182:185], v[86:89]
	v_mfma_f32_16x16x32_bf16 v[82:85], v[158:161], v[182:185], v[82:85]
	v_mfma_f32_16x16x32_bf16 v[70:73], v[150:153], v[214:217], v[70:73]
	v_mfma_f32_16x16x32_bf16 v[66:69], v[158:161], v[214:217], v[66:69]
	s_setprio 0
	s_waitcnt vmcnt(8)
	s_barrier
	s_add_i32 s18, s77, s49
	s_mov_b32 m0, s18
	s_nop 0
	global_load_lds_dwordx4 v192, s[40:41]
	ds_read_b128 v[162:165], v222 offset:16384
	ds_read_b128 v[166:169], v222 offset:17408
	s_add_i32 m0, s18, 0x2000
	s_add_u32 s18, s40, 0x160000
	s_addc_u32 s19, s41, 0
	s_add_i32 s77, s79, s49
	global_load_lds_dwordx4 v208, s[40:41]
	ds_read_b128 v[170:173], v222 offset:18432
	ds_read_b128 v[174:177], v222 offset:19456
	s_mov_b32 m0, s77
	s_nop 0
	global_load_lds_dwordx4 v192, s[18:19]
	ds_read_b128 v[178:181], v222 offset:20480
	ds_read_b128 v[182:185], v222 offset:21504
	s_add_i32 m0, s77, 0x2000
	s_nop 0
	global_load_lds_dwordx4 v208, s[18:19]
	ds_read_b128 v[186:189], v222 offset:22528
	ds_read_b128 v[214:217], v222 offset:23552
	s_mov_b32 m0, s52
	s_nop 0
	global_load_lds_dwordx4 v190, s[42:43]
	s_mov_b32 m0, s53
	s_nop 0
	global_load_lds_dwordx4 v206, s[42:43]
	s_cmp_lg_u32 s10, 0
	s_cbranch_scc1 .Lh0w_g4_2
	s_waitcnt vmcnt(8)
; #define PG8_STAGE(bufoff, gbase, voff) do { _Pragma("unroll") for (int _i = 0; _i < 2; ++_i) \
;         __builtin_amdgcn_global_load_lds((const unsigned*)((const char*)(gbase) + (voff)[_i]), (PG8_LAS unsigned*)(lds + (bufoff) + ldsw + _i * 8192), 16, 0, 0); } while (0)
; #define PG8_LDA(dst, b, h) do { _Pragma("unroll") for (int m = 0; m < 4; ++m) _Pragma("unroll") for (int k = 0; k < 2; ++k) dst[m][k] = *(const PG8_LAS bf16x8*)(lds + PG8_SA(b, h) + aoff + m * 2048 + k * 1024); } while (0)
; #define PG8_LDB(dst, b, h) do { _Pragma("unroll") for (int n = 0; n < 2; ++n) _Pragma("unroll") for (int k = 0; k < 2; ++k) dst[n][k] = *(const PG8_LAS bf16x8*)(lds + PG8_SB(b, h) + boff + n * 2048 + k * 1024); } while (0)
; #define PG8_MMA(ai, bj, At, Bt) do { __builtin_amdgcn_s_setprio(1); _Pragma("unroll") for (int m = 0; m < 4; ++m) _Pragma("unroll") for (int n = 0; n < 2; ++n) _Pragma("unroll") for (int k = 0; k < 2; ++k) \
;         acc[ai][bj][m][n] = __builtin_amdgcn_mfma_f32_16x16x32_bf16(Bt[n][k], At[m][k], acc[ai][bj][m][n], 0, 0, 0); __builtin_amdgcn_s_setprio(0); } while (0)
; #define PG8_WAIT_V(n) asm volatile("s_waitcnt vmcnt(" #n ")" ::: "memory")
; #define PG8_WAIT_L(n) asm volatile("s_waitcnt lgkmcnt(" #n ")" ::: "memory")
; #define PG8_BAR __builtin_amdgcn_s_barrier()
; #define PG8_SCHED __builtin_amdgcn_sched_barrier(0)
; template <class Epi, class Sched, bool ALIGN_EPI = false, bool SP2 = false>
; __device__ __forceinline__ void gemm_phase(PG8_LAS unsigned char* lds, const Gemm g, const Sched& S, const Epi& E, const int wave_id) {
;     ...
;             PG8_WAIT_V(8); PG8_WAIT_L(0); PG8_BAR; PG8_MMA(1, 0, At, B0); PG8_MMA(1, 1, At, B1); PG8_BAR; PG8_SCHED;
;             PG8_LDB(B0, 1, 0); PG8_LDB(B1, 1, 1); PG8_SCHED; PG8_LDA(At, 1, 0); PG8_STAGE(PG8_SA(0, 1), a2 + hstep, voffA);
.Lh0w_g4_2:
	s_waitcnt lgkmcnt(0)
	s_barrier
	s_setprio 1
	s_waitcnt lgkmcnt(0)
	v_mfma_f32_16x16x32_bf16 v[62:65], v[118:121], v[162:165], v[62:65]
	v_mfma_f32_16x16x32_bf16 v[58:61], v[130:133], v[162:165], v[58:61]
	v_mfma_f32_16x16x32_bf16 v[46:49], v[118:121], v[170:173], v[46:49]
	v_mfma_f32_16x16x32_bf16 v[42:45], v[130:133], v[170:173], v[42:45]
	v_mfma_f32_16x16x32_bf16 v[30:33], v[118:121], v[178:181], v[30:33]
	v_mfma_f32_16x16x32_bf16 v[26:29], v[130:133], v[178:181], v[26:29]
	v_mfma_f32_16x16x32_bf16 v[14:17], v[118:121], v[186:189], v[14:17]
	v_mfma_f32_16x16x32_bf16 v[10:13], v[130:133], v[186:189], v[10:13]
	v_mfma_f32_16x16x32_bf16 v[62:65], v[122:125], v[166:169], v[62:65]
	v_mfma_f32_16x16x32_bf16 v[58:61], v[134:137], v[166:169], v[58:61]
	v_mfma_f32_16x16x32_bf16 v[46:49], v[122:125], v[174:177], v[46:49]
	v_mfma_f32_16x16x32_bf16 v[42:45], v[134:137], v[174:177], v[42:45]
	v_mfma_f32_16x16x32_bf16 v[30:33], v[122:125], v[182:185], v[30:33]
	v_mfma_f32_16x16x32_bf16 v[26:29], v[134:137], v[182:185], v[26:29]
	v_mfma_f32_16x16x32_bf16 v[14:17], v[122:125], v[214:217], v[14:17]
	v_mfma_f32_16x16x32_bf16 v[10:13], v[134:137], v[214:217], v[10:13]
	s_setprio 0
	s_setprio 1
	v_mfma_f32_16x16x32_bf16 v[54:57], v[146:149], v[162:165], v[54:57]
	v_mfma_f32_16x16x32_bf16 v[50:53], v[154:157], v[162:165], v[50:53]
	v_mfma_f32_16x16x32_bf16 v[38:41], v[146:149], v[170:173], v[38:41]
	v_mfma_f32_16x16x32_bf16 v[34:37], v[154:157], v[170:173], v[34:37]
	v_mfma_f32_16x16x32_bf16 v[22:25], v[146:149], v[178:181], v[22:25]
	v_mfma_f32_16x16x32_bf16 v[18:21], v[154:157], v[178:181], v[18:21]
	v_mfma_f32_16x16x32_bf16 v[6:9], v[146:149], v[186:189], v[6:9]
	v_mfma_f32_16x16x32_bf16 v[2:5], v[154:157], v[186:189], v[2:5]
	v_mfma_f32_16x16x32_bf16 v[54:57], v[150:153], v[166:169], v[54:57]
	v_mfma_f32_16x16x32_bf16 v[50:53], v[158:161], v[166:169], v[50:53]
	v_mfma_f32_16x16x32_bf16 v[38:41], v[150:153], v[174:177], v[38:41]
	v_mfma_f32_16x16x32_bf16 v[34:37], v[158:161], v[174:177], v[34:37]
	v_mfma_f32_16x16x32_bf16 v[22:25], v[150:153], v[182:185], v[22:25]
	v_mfma_f32_16x16x32_bf16 v[18:21], v[158:161], v[182:185], v[18:21]
	v_mfma_f32_16x16x32_bf16 v[6:9], v[150:153], v[214:217], v[6:9]
	v_mfma_f32_16x16x32_bf16 v[2:5], v[158:161], v[214:217], v[2:5]
	s_setprio 0
	s_waitcnt vmcnt(8)
	s_barrier
	s_add_i32 s77, 0, 0x18000
	s_add_i32 s79, 0, 0x1c000
	s_add_u32 s18, s42, 0x160000
	s_addc_u32 s19, s43, 0
	s_mov_b32 m0, s56
	s_nop 0
	global_load_lds_dwordx4 v190, s[18:19]
	ds_read_b128 v[118:121], v226 offset:32768
	ds_read_b128 v[122:125], v226 offset:33792
	ds_read_b128 v[130:133], v226 offset:34816
	ds_read_b128 v[134:137], v226 offset:35840
	ds_read_b128 v[146:149], v226 offset:49152
	ds_read_b128 v[150:153], v226 offset:50176
	ds_read_b128 v[154:157], v226 offset:51200
	ds_read_b128 v[158:161], v226 offset:52224
	s_mov_b32 m0, s57
	s_nop 0
	global_load_lds_dwordx4 v206, s[18:19]
	ds_read_b128 v[162:165], v222 offset:32768
	ds_read_b128 v[166:169], v222 offset:33792
	ds_read_b128 v[170:173], v222 offset:34816
	ds_read_b128 v[174:177], v222 offset:35840
	ds_read_b128 v[178:181], v222 offset:36864
	ds_read_b128 v[182:185], v222 offset:37888
	ds_read_b128 v[186:189], v222 offset:38912
	ds_read_b128 v[214:217], v222 offset:39936
	s_cmp_lg_u32 s10, 0
	s_cbranch_scc1 .Lh0w_g4_3
	s_waitcnt vmcnt(8)
; #define PG8_STAGE(bufoff, gbase, voff) do { _Pragma("unroll") for (int _i = 0; _i < 2; ++_i) \
;         __builtin_amdgcn_global_load_lds((const unsigned*)((const char*)(gbase) + (voff)[_i]), (PG8_LAS unsigned*)(lds + (bufoff) + ldsw + _i * 8192), 16, 0, 0); } while (0)
; #define PG8_LDA(dst, b, h) do { _Pragma("unroll") for (int m = 0; m < 4; ++m) _Pragma("unroll") for (int k = 0; k < 2; ++k) dst[m][k] = *(const PG8_LAS bf16x8*)(lds + PG8_SA(b, h) + aoff + m * 2048 + k * 1024); } while (0)
; #define PG8_MMA(ai, bj, At, Bt) do { __builtin_amdgcn_s_setprio(1); _Pragma("unroll") for (int m = 0; m < 4; ++m) _Pragma("unroll") for (int n = 0; n < 2; ++n) _Pragma("unroll") for (int k = 0; k < 2; ++k) \
;         acc[ai][bj][m][n] = __builtin_amdgcn_mfma_f32_16x16x32_bf16(Bt[n][k], At[m][k], acc[ai][bj][m][n], 0, 0, 0); __builtin_amdgcn_s_setprio(0); } while (0)
; #define PG8_WAIT_V(n) asm volatile("s_waitcnt vmcnt(" #n ")" ::: "memory")
; #define PG8_WAIT_L(n) asm volatile("s_waitcnt lgkmcnt(" #n ")" ::: "memory")
; #define PG8_BAR __builtin_amdgcn_s_barrier()
; #define PG8_SCHED __builtin_amdgcn_sched_barrier(0)
; template <class Epi, class Sched, bool ALIGN_EPI = false, bool SP2 = false>
; __device__ __forceinline__ void gemm_phase(PG8_LAS unsigned char* lds, const Gemm g, const Sched& S, const Epi& E, const int wave_id) {
;     ...
;             PG8_WAIT_V(8); PG8_WAIT_L(0); PG8_BAR; PG8_MMA(0, 0, At, B0); PG8_MMA(0, 1, At, B1); PG8_BAR; PG8_SCHED;
;             PG8_LDA(At, 1, 1); PG8_STAGE(PG8_SB(1, 0), b3, voffB); PG8_STAGE(PG8_SB(1, 1), b3 + hstep, voffB); PG8_STAGE(PG8_SA(1, 0), a3, voffA);
;             PG8_WAIT_V(8); PG8_WAIT_L(0); PG8_BAR; PG8_MMA(1, 0, At, B0); PG8_MMA(1, 1, At, B1); PG8_BAR; PG8_SCHED;
.Lh0w_g4_3:
	s_waitcnt lgkmcnt(0)
	s_barrier
	s_setprio 1
	s_waitcnt lgkmcnt(0)
	v_mfma_f32_16x16x32_bf16 v[142:145], v[118:121], v[162:165], v[142:145]
	v_mfma_f32_16x16x32_bf16 v[138:141], v[130:133], v[162:165], v[138:141]
	v_mfma_f32_16x16x32_bf16 v[110:113], v[118:121], v[170:173], v[110:113]
	v_mfma_f32_16x16x32_bf16 v[106:109], v[130:133], v[170:173], v[106:109]
	v_mfma_f32_16x16x32_bf16 v[94:97], v[118:121], v[178:181], v[94:97]
	v_mfma_f32_16x16x32_bf16 v[90:93], v[130:133], v[178:181], v[90:93]
	v_mfma_f32_16x16x32_bf16 v[78:81], v[118:121], v[186:189], v[78:81]
	v_mfma_f32_16x16x32_bf16 v[74:77], v[130:133], v[186:189], v[74:77]
	v_mfma_f32_16x16x32_bf16 v[142:145], v[122:125], v[166:169], v[142:145]
	v_mfma_f32_16x16x32_bf16 v[138:141], v[134:137], v[166:169], v[138:141]
	v_mfma_f32_16x16x32_bf16 v[110:113], v[122:125], v[174:177], v[110:113]
	v_mfma_f32_16x16x32_bf16 v[106:109], v[134:137], v[174:177], v[106:109]
	v_mfma_f32_16x16x32_bf16 v[94:97], v[122:125], v[182:185], v[94:97]
	v_mfma_f32_16x16x32_bf16 v[90:93], v[134:137], v[182:185], v[90:93]
	v_mfma_f32_16x16x32_bf16 v[78:81], v[122:125], v[214:217], v[78:81]
	v_mfma_f32_16x16x32_bf16 v[74:77], v[134:137], v[214:217], v[74:77]
	s_setprio 0
	s_setprio 1
	v_mfma_f32_16x16x32_bf16 v[126:129], v[146:149], v[162:165], v[126:129]
	v_mfma_f32_16x16x32_bf16 v[114:117], v[154:157], v[162:165], v[114:117]
	v_mfma_f32_16x16x32_bf16 v[102:105], v[146:149], v[170:173], v[102:105]
	v_mfma_f32_16x16x32_bf16 v[98:101], v[154:157], v[170:173], v[98:101]
	v_mfma_f32_16x16x32_bf16 v[86:89], v[146:149], v[178:181], v[86:89]
	v_mfma_f32_16x16x32_bf16 v[82:85], v[154:157], v[178:181], v[82:85]
	v_mfma_f32_16x16x32_bf16 v[70:73], v[146:149], v[186:189], v[70:73]
	v_mfma_f32_16x16x32_bf16 v[66:69], v[154:157], v[186:189], v[66:69]
	v_mfma_f32_16x16x32_bf16 v[126:129], v[150:153], v[166:169], v[126:129]
	v_mfma_f32_16x16x32_bf16 v[114:117], v[158:161], v[166:169], v[114:117]
	v_mfma_f32_16x16x32_bf16 v[102:105], v[150:153], v[174:177], v[102:105]
	v_mfma_f32_16x16x32_bf16 v[98:101], v[158:161], v[174:177], v[98:101]
	v_mfma_f32_16x16x32_bf16 v[86:89], v[150:153], v[182:185], v[86:89]
	v_mfma_f32_16x16x32_bf16 v[82:85], v[158:161], v[182:185], v[82:85]
	v_mfma_f32_16x16x32_bf16 v[70:73], v[150:153], v[214:217], v[70:73]
	v_mfma_f32_16x16x32_bf16 v[66:69], v[158:161], v[214:217], v[66:69]
	s_setprio 0
	s_waitcnt vmcnt(8)
	s_barrier
	s_add_u32 vcc_lo, s42, 0x80
	s_addc_u32 vcc_hi, s43, 0
	s_mov_b32 m0, s68
	s_nop 0
	global_load_lds_dwordx4 v190, vcc
	ds_read_b128 v[162:165], v222 offset:49152
	ds_read_b128 v[166:169], v222 offset:50176
	s_mov_b32 m0, s69
	s_add_i32 s18, s77, s49
	global_load_lds_dwordx4 v206, vcc
	ds_read_b128 v[170:173], v222 offset:51200
	ds_read_b128 v[174:177], v222 offset:52224
	s_add_u32 vcc_lo, s40, 0x80
	s_addc_u32 vcc_hi, s41, 0
	s_mov_b32 m0, s18
	s_nop 0
	global_load_lds_dwordx4 v192, vcc
	ds_read_b128 v[178:181], v222 offset:53248
	ds_read_b128 v[182:185], v222 offset:54272
	s_add_i32 m0, s18, 0x2000
	s_add_u32 s18, s40, 0x160080
	s_addc_u32 s19, s41, 0
	global_load_lds_dwordx4 v208, vcc
	ds_read_b128 v[186:189], v222 offset:55296
	ds_read_b128 v[214:217], v222 offset:56320
	s_add_i32 s40, s79, s49
	s_mov_b32 m0, s40
	s_nop 0
	global_load_lds_dwordx4 v192, s[18:19]
	s_add_i32 m0, s40, 0x2000
	s_nop 0
	global_load_lds_dwordx4 v208, s[18:19]
	s_cmp_lg_u32 s10, 0
	s_cbranch_scc1 .Lh0w_g4_4
	s_waitcnt vmcnt(8)
.Lh0w_g4_4:
	s_waitcnt lgkmcnt(0)
	s_barrier
	s_setprio 1
	s_waitcnt lgkmcnt(0)
	v_mfma_f32_16x16x32_bf16 v[62:65], v[118:121], v[162:165], v[62:65]
	v_mfma_f32_16x16x32_bf16 v[58:61], v[130:133], v[162:165], v[58:61]
	v_mfma_f32_16x16x32_bf16 v[46:49], v[118:121], v[170:173], v[46:49]
	v_mfma_f32_16x16x32_bf16 v[42:45], v[130:133], v[170:173], v[42:45]
	v_mfma_f32_16x16x32_bf16 v[30:33], v[118:121], v[178:181], v[30:33]
	v_mfma_f32_16x16x32_bf16 v[26:29], v[130:133], v[178:181], v[26:29]
	v_mfma_f32_16x16x32_bf16 v[14:17], v[118:121], v[186:189], v[14:17]
	v_mfma_f32_16x16x32_bf16 v[10:13], v[130:133], v[186:189], v[10:13]
	v_mfma_f32_16x16x32_bf16 v[62:65], v[122:125], v[166:169], v[62:65]
	v_mfma_f32_16x16x32_bf16 v[58:61], v[134:137], v[166:169], v[58:61]
	v_mfma_f32_16x16x32_bf16 v[46:49], v[122:125], v[174:177], v[46:49]
	v_mfma_f32_16x16x32_bf16 v[42:45], v[134:137], v[174:177], v[42:45]
	v_mfma_f32_16x16x32_bf16 v[30:33], v[122:125], v[182:185], v[30:33]
	v_mfma_f32_16x16x32_bf16 v[26:29], v[134:137], v[182:185], v[26:29]
	v_mfma_f32_16x16x32_bf16 v[14:17], v[122:125], v[214:217], v[14:17]
	v_mfma_f32_16x16x32_bf16 v[10:13], v[134:137], v[214:217], v[10:13]
	s_setprio 0
	s_setprio 1
	v_mfma_f32_16x16x32_bf16 v[54:57], v[146:149], v[162:165], v[54:57]
	v_mfma_f32_16x16x32_bf16 v[50:53], v[154:157], v[162:165], v[50:53]
	v_mfma_f32_16x16x32_bf16 v[38:41], v[146:149], v[170:173], v[38:41]
	v_mfma_f32_16x16x32_bf16 v[34:37], v[154:157], v[170:173], v[34:37]
	v_mfma_f32_16x16x32_bf16 v[22:25], v[146:149], v[178:181], v[22:25]
	v_mfma_f32_16x16x32_bf16 v[18:21], v[154:157], v[178:181], v[18:21]
	v_mfma_f32_16x16x32_bf16 v[6:9], v[146:149], v[186:189], v[6:9]
	v_mfma_f32_16x16x32_bf16 v[2:5], v[154:157], v[186:189], v[2:5]
	v_mfma_f32_16x16x32_bf16 v[54:57], v[150:153], v[166:169], v[54:57]
	v_mfma_f32_16x16x32_bf16 v[50:53], v[158:161], v[166:169], v[50:53]
	v_mfma_f32_16x16x32_bf16 v[38:41], v[150:153], v[174:177], v[38:41]
	v_mfma_f32_16x16x32_bf16 v[34:37], v[158:161], v[174:177], v[34:37]
	v_mfma_f32_16x16x32_bf16 v[22:25], v[150:153], v[182:185], v[22:25]
	v_mfma_f32_16x16x32_bf16 v[18:21], v[158:161], v[182:185], v[18:21]
	v_mfma_f32_16x16x32_bf16 v[6:9], v[150:153], v[214:217], v[6:9]
	v_mfma_f32_16x16x32_bf16 v[2:5], v[158:161], v[214:217], v[2:5]
	s_setprio 0
	s_waitcnt vmcnt(8)
	s_barrier
	s_add_i32 s76, s76, 2
	s_add_u32 s74, s74, 0x100
	s_addc_u32 s75, s75, 0
	s_cmpk_gt_u32 s76, 0x55
	s_mov_b64 s[18:19], s[20:21]
	s_cbranch_scc0 .LBB0_759
	s_and_b64 vcc, exec, s[10:11]
	s_cbranch_vccz .LBB0_762
	s_barrier

; #define PG8_STAGE(bufoff, gbase, voff) do { _Pragma("unroll") for (int _i = 0; _i < 2; ++_i) \
;         __builtin_amdgcn_global_load_lds((const unsigned*)((const char*)(gbase) + (voff)[_i]), (PG8_LAS unsigned*)(lds + (bufoff) + ldsw + _i * 8192), 16, 0, 0); } while (0)
; #define PG8_LDA(dst, b, h) do { _Pragma("unroll") for (int m = 0; m < 4; ++m) _Pragma("unroll") for (int k = 0; k < 2; ++k) dst[m][k] = *(const PG8_LAS bf16x8*)(lds + PG8_SA(b, h) + aoff + m * 2048 + k * 1024); } while (0)
; #define PG8_LDB(dst, b, h) do { _Pragma("unroll") for (int n = 0; n < 2; ++n) _Pragma("unroll") for (int k = 0; k < 2; ++k) dst[n][k] = *(const PG8_LAS bf16x8*)(lds + PG8_SB(b, h) + boff + n * 2048 + k * 1024); } while (0)
; #define PG8_MMA(ai, bj, At, Bt) do { __builtin_amdgcn_s_setprio(1); _Pragma("unroll") for (int m = 0; m < 4; ++m) _Pragma("unroll") for (int n = 0; n < 2; ++n) _Pragma("unroll") for (int k = 0; k < 2; ++k) \
;         acc[ai][bj][m][n] = __builtin_amdgcn_mfma_f32_16x16x32_bf16(Bt[n][k], At[m][k], acc[ai][bj][m][n], 0, 0, 0); __builtin_amdgcn_s_setprio(0); } while (0)
; #define PG8_WAIT_V(n) asm volatile("s_waitcnt vmcnt(" #n ")" ::: "memory")
; #define PG8_WAIT_L(n) asm volatile("s_waitcnt lgkmcnt(" #n ")" ::: "memory")
; #define PG8_BAR __builtin_amdgcn_s_barrier()
; #define PG8_SCHED __builtin_amdgcn_sched_barrier(0)
; template <class Epi, class Sched, bool ALIGN_EPI = false, bool SP2 = false>
; __device__ __forceinline__ void gemm_phase(PG8_LAS unsigned char* lds, const Gemm g, const Sched& S, const Epi& E, const int wave_id) {
;     ...
;             PG8_LDB(B0, 0, 0); PG8_LDB(B1, 0, 1); PG8_SCHED; PG8_LDA(At, 0, 0); PG8_STAGE(PG8_SA(1, 1), a1 + hstep, voffA);
;             PG8_WAIT_V(8); PG8_WAIT_L(0); PG8_BAR; PG8_MMA(0, 0, At, B0); PG8_MMA(0, 1, At, B1); PG8_BAR; PG8_SCHED;
;             PG8_LDA(At, 0, 1); PG8_STAGE(PG8_SB(0, 0), b2, voffB); PG8_STAGE(PG8_SB(0, 1), b2 + hstep, voffB); PG8_STAGE(PG8_SA(0, 0), a2, voffA);
;             PG8_WAIT_V(8); PG8_WAIT_L(0); PG8_BAR; PG8_MMA(1, 0, At, B0); PG8_MMA(1, 1, At, B1); PG8_BAR; PG8_SCHED;
.LBB0_904:
	s_add_u32 s52, s46, 0xfff80080
	s_addc_u32 s53, s47, -1
	s_add_i32 s85, 0, 0x10000
	s_cmp_eq_u32 s84, 28
	s_cselect_b32 s83, s21, s53
	s_cselect_b32 s82, s49, s52
	s_cselect_b32 s53, s19, s81
	s_cselect_b32 s52, s79, s80
	s_add_i32 s92, 0, 0x14000
	s_add_i32 m0, s70, 0xc000
	s_nop 0
	global_load_lds_dwordx4 v214, s[46:47]
	ds_read_b128 v[114:117], v226
	ds_read_b128 v[118:121], v226 offset:1024
	ds_read_b128 v[130:133], v226 offset:2048
	ds_read_b128 v[134:137], v226 offset:3072
	ds_read_b128 v[138:141], v226 offset:16384
	ds_read_b128 v[142:145], v226 offset:17408
	ds_read_b128 v[146:149], v226 offset:18432
	ds_read_b128 v[150:153], v226 offset:19456
	s_add_i32 m0, s70, 0xe000
	s_nop 0
	global_load_lds_dwordx4 v216, s[46:47]
	ds_read_b128 v[162:165], v244
	ds_read_b128 v[166:169], v244 offset:1024
	ds_read_b128 v[170:173], v244 offset:2048
	ds_read_b128 v[174:177], v244 offset:3072
	ds_read_b128 v[178:181], v244 offset:4096
	ds_read_b128 v[182:185], v244 offset:5120
	ds_read_b128 v[186:189], v244 offset:6144
	ds_read_b128 v[190:193], v244 offset:7168
	s_cmp_lg_u32 s16, 0
	s_cbranch_scc1 .Lh0w_g5_1
	s_waitcnt vmcnt(8)
.Lh0w_g5_1:
	s_waitcnt lgkmcnt(0)
	s_barrier
	s_setprio 1
	s_waitcnt lgkmcnt(0)
	v_mfma_f32_16x16x32_bf16 v[158:161], v[114:117], v[162:165], v[158:161]
	v_mfma_f32_16x16x32_bf16 v[154:157], v[130:133], v[162:165], v[154:157]
	v_mfma_f32_16x16x32_bf16 v[110:113], v[114:117], v[170:173], v[110:113]
	v_mfma_f32_16x16x32_bf16 v[106:109], v[130:133], v[170:173], v[106:109]
	v_mfma_f32_16x16x32_bf16 v[94:97], v[114:117], v[178:181], v[94:97]
	v_mfma_f32_16x16x32_bf16 v[90:93], v[130:133], v[178:181], v[90:93]
	v_mfma_f32_16x16x32_bf16 v[78:81], v[114:117], v[186:189], v[78:81]
	v_mfma_f32_16x16x32_bf16 v[74:77], v[130:133], v[186:189], v[74:77]
	v_mfma_f32_16x16x32_bf16 v[158:161], v[118:121], v[166:169], v[158:161]
	v_mfma_f32_16x16x32_bf16 v[154:157], v[134:137], v[166:169], v[154:157]
	v_mfma_f32_16x16x32_bf16 v[110:113], v[118:121], v[174:177], v[110:113]
	v_mfma_f32_16x16x32_bf16 v[106:109], v[134:137], v[174:177], v[106:109]
	v_mfma_f32_16x16x32_bf16 v[94:97], v[118:121], v[182:185], v[94:97]
	v_mfma_f32_16x16x32_bf16 v[90:93], v[134:137], v[182:185], v[90:93]
	v_mfma_f32_16x16x32_bf16 v[78:81], v[118:121], v[190:193], v[78:81]
	v_mfma_f32_16x16x32_bf16 v[74:77], v[134:137], v[190:193], v[74:77]
	s_setprio 0
	s_setprio 1
	v_mfma_f32_16x16x32_bf16 v[126:129], v[138:141], v[162:165], v[126:129]
	v_mfma_f32_16x16x32_bf16 v[122:125], v[146:149], v[162:165], v[122:125]
	v_mfma_f32_16x16x32_bf16 v[102:105], v[138:141], v[170:173], v[102:105]
	v_mfma_f32_16x16x32_bf16 v[98:101], v[146:149], v[170:173], v[98:101]
	v_mfma_f32_16x16x32_bf16 v[86:89], v[138:141], v[178:181], v[86:89]
	v_mfma_f32_16x16x32_bf16 v[82:85], v[146:149], v[178:181], v[82:85]
	v_mfma_f32_16x16x32_bf16 v[70:73], v[138:141], v[186:189], v[70:73]
	v_mfma_f32_16x16x32_bf16 v[66:69], v[146:149], v[186:189], v[66:69]
	v_mfma_f32_16x16x32_bf16 v[126:129], v[142:145], v[166:169], v[126:129]
	v_mfma_f32_16x16x32_bf16 v[122:125], v[150:153], v[166:169], v[122:125]
	v_mfma_f32_16x16x32_bf16 v[102:105], v[142:145], v[174:177], v[102:105]
	v_mfma_f32_16x16x32_bf16 v[98:101], v[150:153], v[174:177], v[98:101]
	v_mfma_f32_16x16x32_bf16 v[86:89], v[142:145], v[182:185], v[86:89]
	v_mfma_f32_16x16x32_bf16 v[82:85], v[150:153], v[182:185], v[82:85]
	v_mfma_f32_16x16x32_bf16 v[70:73], v[142:145], v[190:193], v[70:73]
	v_mfma_f32_16x16x32_bf16 v[66:69], v[150:153], v[190:193], v[66:69]
	s_setprio 0
	s_waitcnt vmcnt(8)
	s_barrier
	s_add_i32 s85, s85, s69
	s_mov_b32 m0, s85
	s_nop 0
	global_load_lds_dwordx4 v208, s[52:53]
	ds_read_b128 v[162:165], v244 offset:16384
	ds_read_b128 v[166:169], v244 offset:17408
	s_add_i32 m0, s85, 0x2000
	s_add_u32 s88, s52, 0x80000
	s_addc_u32 s89, s53, 0
	s_add_i32 s85, s92, s69
	global_load_lds_dwordx4 v212, s[52:53]
	ds_read_b128 v[170:173], v244 offset:18432
	ds_read_b128 v[174:177], v244 offset:19456
	s_mov_b32 m0, s85
	s_nop 0
	global_load_lds_dwordx4 v208, s[88:89]
	ds_read_b128 v[178:181], v244 offset:20480
	ds_read_b128 v[182:185], v244 offset:21504
	s_add_i32 m0, s85, 0x2000
	s_nop 0
	global_load_lds_dwordx4 v212, s[88:89]
	ds_read_b128 v[186:189], v244 offset:22528
	ds_read_b128 v[190:193], v244 offset:23552
	s_mov_b32 m0, s70
	s_nop 0
	global_load_lds_dwordx4 v206, s[82:83]
	s_mov_b32 m0, s71
	s_nop 0
	global_load_lds_dwordx4 v210, s[82:83]
	s_cmp_lg_u32 s16, 0
	s_cbranch_scc1 .Lh0w_g5_2
	s_waitcnt vmcnt(8)
; #define PG8_STAGE(bufoff, gbase, voff) do { _Pragma("unroll") for (int _i = 0; _i < 2; ++_i) \
;         __builtin_amdgcn_global_load_lds((const unsigned*)((const char*)(gbase) + (voff)[_i]), (PG8_LAS unsigned*)(lds + (bufoff) + ldsw + _i * 8192), 16, 0, 0); } while (0)
; #define PG8_LDA(dst, b, h) do { _Pragma("unroll") for (int m = 0; m < 4; ++m) _Pragma("unroll") for (int k = 0; k < 2; ++k) dst[m][k] = *(const PG8_LAS bf16x8*)(lds + PG8_SA(b, h) + aoff + m * 2048 + k * 1024); } while (0)
; #define PG8_LDB(dst, b, h) do { _Pragma("unroll") for (int n = 0; n < 2; ++n) _Pragma("unroll") for (int k = 0; k < 2; ++k) dst[n][k] = *(const PG8_LAS bf16x8*)(lds + PG8_SB(b, h) + boff + n * 2048 + k * 1024); } while (0)
; #define PG8_MMA(ai, bj, At, Bt) do { __builtin_amdgcn_s_setprio(1); _Pragma("unroll") for (int m = 0; m < 4; ++m) _Pragma("unroll") for (int n = 0; n < 2; ++n) _Pragma("unroll") for (int k = 0; k < 2; ++k) \
;         acc[ai][bj][m][n] = __builtin_amdgcn_mfma_f32_16x16x32_bf16(Bt[n][k], At[m][k], acc[ai][bj][m][n], 0, 0, 0); __builtin_amdgcn_s_setprio(0); } while (0)
; #define PG8_WAIT_V(n) asm volatile("s_waitcnt vmcnt(" #n ")" ::: "memory")
; #define PG8_WAIT_L(n) asm volatile("s_waitcnt lgkmcnt(" #n ")" ::: "memory")
; #define PG8_BAR __builtin_amdgcn_s_barrier()
; #define PG8_SCHED __builtin_amdgcn_sched_barrier(0)
; template <class Epi, class Sched, bool ALIGN_EPI = false, bool SP2 = false>
; __device__ __forceinline__ void gemm_phase(PG8_LAS unsigned char* lds, const Gemm g, const Sched& S, const Epi& E, const int wave_id) {
;     ...
;             PG8_WAIT_V(8); PG8_WAIT_L(0); PG8_BAR; PG8_MMA(1, 0, At, B0); PG8_MMA(1, 1, At, B1); PG8_BAR; PG8_SCHED;
;             PG8_LDB(B0, 1, 0); PG8_LDB(B1, 1, 1); PG8_SCHED; PG8_LDA(At, 1, 0); PG8_STAGE(PG8_SA(0, 1), a2 + hstep, voffA);
.Lh0w_g5_2:
	s_waitcnt lgkmcnt(0)
	s_barrier
	s_setprio 1
	s_waitcnt lgkmcnt(0)
	v_mfma_f32_16x16x32_bf16 v[62:65], v[114:117], v[162:165], v[62:65]
	v_mfma_f32_16x16x32_bf16 v[58:61], v[130:133], v[162:165], v[58:61]
	v_mfma_f32_16x16x32_bf16 v[46:49], v[114:117], v[170:173], v[46:49]
	v_mfma_f32_16x16x32_bf16 v[42:45], v[130:133], v[170:173], v[42:45]
	v_mfma_f32_16x16x32_bf16 v[30:33], v[114:117], v[178:181], v[30:33]
	v_mfma_f32_16x16x32_bf16 v[26:29], v[130:133], v[178:181], v[26:29]
	v_mfma_f32_16x16x32_bf16 v[14:17], v[114:117], v[186:189], v[14:17]
	v_mfma_f32_16x16x32_bf16 v[10:13], v[130:133], v[186:189], v[10:13]
	v_mfma_f32_16x16x32_bf16 v[62:65], v[118:121], v[166:169], v[62:65]
	v_mfma_f32_16x16x32_bf16 v[58:61], v[134:137], v[166:169], v[58:61]
	v_mfma_f32_16x16x32_bf16 v[46:49], v[118:121], v[174:177], v[46:49]
	v_mfma_f32_16x16x32_bf16 v[42:45], v[134:137], v[174:177], v[42:45]
	v_mfma_f32_16x16x32_bf16 v[30:33], v[118:121], v[182:185], v[30:33]
	v_mfma_f32_16x16x32_bf16 v[26:29], v[134:137], v[182:185], v[26:29]
	v_mfma_f32_16x16x32_bf16 v[14:17], v[118:121], v[190:193], v[14:17]
	v_mfma_f32_16x16x32_bf16 v[10:13], v[134:137], v[190:193], v[10:13]
	s_setprio 0
	s_setprio 1
	v_mfma_f32_16x16x32_bf16 v[54:57], v[138:141], v[162:165], v[54:57]
	v_mfma_f32_16x16x32_bf16 v[50:53], v[146:149], v[162:165], v[50:53]
	v_mfma_f32_16x16x32_bf16 v[38:41], v[138:141], v[170:173], v[38:41]
	v_mfma_f32_16x16x32_bf16 v[34:37], v[146:149], v[170:173], v[34:37]
	v_mfma_f32_16x16x32_bf16 v[22:25], v[138:141], v[178:181], v[22:25]
	v_mfma_f32_16x16x32_bf16 v[18:21], v[146:149], v[178:181], v[18:21]
	v_mfma_f32_16x16x32_bf16 v[6:9], v[138:141], v[186:189], v[6:9]
	v_mfma_f32_16x16x32_bf16 v[2:5], v[146:149], v[186:189], v[2:5]
	v_mfma_f32_16x16x32_bf16 v[54:57], v[142:145], v[166:169], v[54:57]
	v_mfma_f32_16x16x32_bf16 v[50:53], v[150:153], v[166:169], v[50:53]
	v_mfma_f32_16x16x32_bf16 v[38:41], v[142:145], v[174:177], v[38:41]
	v_mfma_f32_16x16x32_bf16 v[34:37], v[150:153], v[174:177], v[34:37]
	v_mfma_f32_16x16x32_bf16 v[22:25], v[142:145], v[182:185], v[22:25]
	v_mfma_f32_16x16x32_bf16 v[18:21], v[150:153], v[182:185], v[18:21]
	v_mfma_f32_16x16x32_bf16 v[6:9], v[142:145], v[190:193], v[6:9]
	v_mfma_f32_16x16x32_bf16 v[2:5], v[150:153], v[190:193], v[2:5]
	s_setprio 0
	s_waitcnt vmcnt(8)
	s_barrier
	s_add_i32 s85, 0, 0x18000
	s_add_i32 s88, 0, 0x1c000
	s_add_u32 s82, s82, 0x80000
	s_addc_u32 s83, s83, 0
	s_mov_b32 m0, s72
	s_nop 0
	global_load_lds_dwordx4 v206, s[82:83]
	ds_read_b128 v[114:117], v226 offset:32768
	ds_read_b128 v[118:121], v226 offset:33792
	ds_read_b128 v[130:133], v226 offset:34816
	ds_read_b128 v[134:137], v226 offset:35840
	ds_read_b128 v[138:141], v226 offset:49152
	ds_read_b128 v[142:145], v226 offset:50176
	ds_read_b128 v[146:149], v226 offset:51200
	ds_read_b128 v[150:153], v226 offset:52224
	s_mov_b32 m0, s73
	s_nop 0
	global_load_lds_dwordx4 v210, s[82:83]
	ds_read_b128 v[162:165], v244 offset:32768
	ds_read_b128 v[166:169], v244 offset:33792
	ds_read_b128 v[170:173], v244 offset:34816
	ds_read_b128 v[174:177], v244 offset:35840
	ds_read_b128 v[178:181], v244 offset:36864
	ds_read_b128 v[182:185], v244 offset:37888
	ds_read_b128 v[186:189], v244 offset:38912
	ds_read_b128 v[190:193], v244 offset:39936
	s_cmp_lg_u32 s16, 0
	s_cbranch_scc1 .Lh0w_g5_3
	s_waitcnt vmcnt(8)
; #define PG8_STAGE(bufoff, gbase, voff) do { _Pragma("unroll") for (int _i = 0; _i < 2; ++_i) \
;         __builtin_amdgcn_global_load_lds((const unsigned*)((const char*)(gbase) + (voff)[_i]), (PG8_LAS unsigned*)(lds + (bufoff) + ldsw + _i * 8192), 16, 0, 0); } while (0)
; #define PG8_LDA(dst, b, h) do { _Pragma("unroll") for (int m = 0; m < 4; ++m) _Pragma("unroll") for (int k = 0; k < 2; ++k) dst[m][k] = *(const PG8_LAS bf16x8*)(lds + PG8_SA(b, h) + aoff + m * 2048 + k * 1024); } while (0)
; #define PG8_MMA(ai, bj, At, Bt) do { __builtin_amdgcn_s_setprio(1); _Pragma("unroll") for (int m = 0; m < 4; ++m) _Pragma("unroll") for (int n = 0; n < 2; ++n) _Pragma("unroll") for (int k = 0; k < 2; ++k) \
;         acc[ai][bj][m][n] = __builtin_amdgcn_mfma_f32_16x16x32_bf16(Bt[n][k], At[m][k], acc[ai][bj][m][n], 0, 0, 0); __builtin_amdgcn_s_setprio(0); } while (0)
; #define PG8_WAIT_V(n) asm volatile("s_waitcnt vmcnt(" #n ")" ::: "memory")
; #define PG8_WAIT_L(n) asm volatile("s_waitcnt lgkmcnt(" #n ")" ::: "memory")
; #define PG8_BAR __builtin_amdgcn_s_barrier()
; #define PG8_SCHED __builtin_amdgcn_sched_barrier(0)
; template <class Epi, class Sched, bool ALIGN_EPI = false, bool SP2 = false>
; __device__ __forceinline__ void gemm_phase(PG8_LAS unsigned char* lds, const Gemm g, const Sched& S, const Epi& E, const int wave_id) {
;     ...
;             PG8_WAIT_V(8); PG8_WAIT_L(0); PG8_BAR; PG8_MMA(0, 0, At, B0); PG8_MMA(0, 1, At, B1); PG8_BAR; PG8_SCHED;
;             PG8_LDA(At, 1, 1); PG8_STAGE(PG8_SB(1, 0), b3, voffB); PG8_STAGE(PG8_SB(1, 1), b3 + hstep, voffB); PG8_STAGE(PG8_SA(1, 0), a3, voffA);
;             PG8_WAIT_V(8); PG8_WAIT_L(0); PG8_BAR; PG8_MMA(1, 0, At, B0); PG8_MMA(1, 1, At, B1); PG8_BAR; PG8_SCHED;
.Lh0w_g5_3:
	s_waitcnt lgkmcnt(0)
	s_barrier
	s_setprio 1
	s_waitcnt lgkmcnt(0)
	v_mfma_f32_16x16x32_bf16 v[158:161], v[114:117], v[162:165], v[158:161]
	v_mfma_f32_16x16x32_bf16 v[154:157], v[130:133], v[162:165], v[154:157]
	v_mfma_f32_16x16x32_bf16 v[110:113], v[114:117], v[170:173], v[110:113]
	v_mfma_f32_16x16x32_bf16 v[106:109], v[130:133], v[170:173], v[106:109]
	v_mfma_f32_16x16x32_bf16 v[94:97], v[114:117], v[178:181], v[94:97]
	v_mfma_f32_16x16x32_bf16 v[90:93], v[130:133], v[178:181], v[90:93]
	v_mfma_f32_16x16x32_bf16 v[78:81], v[114:117], v[186:189], v[78:81]
	v_mfma_f32_16x16x32_bf16 v[74:77], v[130:133], v[186:189], v[74:77]
	v_mfma_f32_16x16x32_bf16 v[158:161], v[118:121], v[166:169], v[158:161]
	v_mfma_f32_16x16x32_bf16 v[154:157], v[134:137], v[166:169], v[154:157]
	v_mfma_f32_16x16x32_bf16 v[110:113], v[118:121], v[174:177], v[110:113]
	v_mfma_f32_16x16x32_bf16 v[106:109], v[134:137], v[174:177], v[106:109]
	v_mfma_f32_16x16x32_bf16 v[94:97], v[118:121], v[182:185], v[94:97]
	v_mfma_f32_16x16x32_bf16 v[90:93], v[134:137], v[182:185], v[90:93]
	v_mfma_f32_16x16x32_bf16 v[78:81], v[118:121], v[190:193], v[78:81]
	v_mfma_f32_16x16x32_bf16 v[74:77], v[134:137], v[190:193], v[74:77]
	s_setprio 0
	s_setprio 1
	v_mfma_f32_16x16x32_bf16 v[126:129], v[138:141], v[162:165], v[126:129]
	v_mfma_f32_16x16x32_bf16 v[122:125], v[146:149], v[162:165], v[122:125]
	v_mfma_f32_16x16x32_bf16 v[102:105], v[138:141], v[170:173], v[102:105]
	v_mfma_f32_16x16x32_bf16 v[98:101], v[146:149], v[170:173], v[98:101]
	v_mfma_f32_16x16x32_bf16 v[86:89], v[138:141], v[178:181], v[86:89]
	v_mfma_f32_16x16x32_bf16 v[82:85], v[146:149], v[178:181], v[82:85]
	v_mfma_f32_16x16x32_bf16 v[70:73], v[138:141], v[186:189], v[70:73]
	v_mfma_f32_16x16x32_bf16 v[66:69], v[146:149], v[186:189], v[66:69]
	v_mfma_f32_16x16x32_bf16 v[126:129], v[142:145], v[166:169], v[126:129]
	v_mfma_f32_16x16x32_bf16 v[122:125], v[150:153], v[166:169], v[122:125]
	v_mfma_f32_16x16x32_bf16 v[102:105], v[142:145], v[174:177], v[102:105]
	v_mfma_f32_16x16x32_bf16 v[98:101], v[150:153], v[174:177], v[98:101]
	v_mfma_f32_16x16x32_bf16 v[86:89], v[142:145], v[182:185], v[86:89]
	v_mfma_f32_16x16x32_bf16 v[82:85], v[150:153], v[182:185], v[82:85]
	v_mfma_f32_16x16x32_bf16 v[70:73], v[142:145], v[190:193], v[70:73]
	v_mfma_f32_16x16x32_bf16 v[66:69], v[150:153], v[190:193], v[66:69]
	s_setprio 0
	s_waitcnt vmcnt(8)
	s_barrier
	s_add_u32 vcc_lo, s82, 0xfff80080
	s_addc_u32 vcc_hi, s83, -1
	s_mov_b32 m0, s76
	s_nop 0
	global_load_lds_dwordx4 v206, vcc
	ds_read_b128 v[162:165], v244 offset:49152
	ds_read_b128 v[166:169], v244 offset:50176
	s_mov_b32 m0, s77
	s_add_i32 s82, s85, s69
	global_load_lds_dwordx4 v210, vcc
	ds_read_b128 v[170:173], v244 offset:51200
	ds_read_b128 v[174:177], v244 offset:52224
	s_add_u32 vcc_lo, s52, 0x80
	s_addc_u32 vcc_hi, s53, 0
	s_mov_b32 m0, s82
	s_nop 0
	global_load_lds_dwordx4 v208, vcc
	ds_read_b128 v[178:181], v244 offset:53248
	ds_read_b128 v[182:185], v244 offset:54272
	s_add_i32 m0, s82, 0x2000
	s_add_u32 s52, s52, 0x80080
	s_addc_u32 s53, s53, 0
	global_load_lds_dwordx4 v212, vcc
	ds_read_b128 v[186:189], v244 offset:55296
	ds_read_b128 v[190:193], v244 offset:56320
	s_add_i32 s82, s88, s69
	s_mov_b32 m0, s82
	s_nop 0
	global_load_lds_dwordx4 v208, s[52:53]
	s_add_i32 m0, s82, 0x2000
	s_nop 0
	global_load_lds_dwordx4 v212, s[52:53]
	s_cmp_lg_u32 s16, 0
	s_cbranch_scc1 .Lh0w_g5_4
	s_waitcnt vmcnt(8)
.Lh0w_g5_4:
	s_waitcnt lgkmcnt(0)
	s_barrier
	s_setprio 1
	s_waitcnt lgkmcnt(0)
	v_mfma_f32_16x16x32_bf16 v[62:65], v[114:117], v[162:165], v[62:65]
	v_mfma_f32_16x16x32_bf16 v[58:61], v[130:133], v[162:165], v[58:61]
	v_mfma_f32_16x16x32_bf16 v[46:49], v[114:117], v[170:173], v[46:49]
	v_mfma_f32_16x16x32_bf16 v[42:45], v[130:133], v[170:173], v[42:45]
	v_mfma_f32_16x16x32_bf16 v[30:33], v[114:117], v[178:181], v[30:33]
	v_mfma_f32_16x16x32_bf16 v[26:29], v[130:133], v[178:181], v[26:29]
	v_mfma_f32_16x16x32_bf16 v[14:17], v[114:117], v[186:189], v[14:17]
	v_mfma_f32_16x16x32_bf16 v[10:13], v[130:133], v[186:189], v[10:13]
	v_mfma_f32_16x16x32_bf16 v[62:65], v[118:121], v[166:169], v[62:65]
	v_mfma_f32_16x16x32_bf16 v[58:61], v[134:137], v[166:169], v[58:61]
	v_mfma_f32_16x16x32_bf16 v[46:49], v[118:121], v[174:177], v[46:49]
	v_mfma_f32_16x16x32_bf16 v[42:45], v[134:137], v[174:177], v[42:45]
	v_mfma_f32_16x16x32_bf16 v[30:33], v[118:121], v[182:185], v[30:33]
	v_mfma_f32_16x16x32_bf16 v[26:29], v[134:137], v[182:185], v[26:29]
	v_mfma_f32_16x16x32_bf16 v[14:17], v[118:121], v[190:193], v[14:17]
	v_mfma_f32_16x16x32_bf16 v[10:13], v[134:137], v[190:193], v[10:13]
	s_setprio 0
	s_setprio 1
	v_mfma_f32_16x16x32_bf16 v[54:57], v[138:141], v[162:165], v[54:57]
	v_mfma_f32_16x16x32_bf16 v[50:53], v[146:149], v[162:165], v[50:53]
	v_mfma_f32_16x16x32_bf16 v[38:41], v[138:141], v[170:173], v[38:41]
	v_mfma_f32_16x16x32_bf16 v[34:37], v[146:149], v[170:173], v[34:37]
	v_mfma_f32_16x16x32_bf16 v[22:25], v[138:141], v[178:181], v[22:25]
	v_mfma_f32_16x16x32_bf16 v[18:21], v[146:149], v[178:181], v[18:21]
	v_mfma_f32_16x16x32_bf16 v[6:9], v[138:141], v[186:189], v[6:9]
	v_mfma_f32_16x16x32_bf16 v[2:5], v[146:149], v[186:189], v[2:5]
	v_mfma_f32_16x16x32_bf16 v[54:57], v[142:145], v[166:169], v[54:57]
	v_mfma_f32_16x16x32_bf16 v[50:53], v[150:153], v[166:169], v[50:53]
	v_mfma_f32_16x16x32_bf16 v[38:41], v[142:145], v[174:177], v[38:41]
	v_mfma_f32_16x16x32_bf16 v[34:37], v[150:153], v[174:177], v[34:37]
	v_mfma_f32_16x16x32_bf16 v[22:25], v[142:145], v[182:185], v[22:25]
	v_mfma_f32_16x16x32_bf16 v[18:21], v[150:153], v[182:185], v[18:21]
	v_mfma_f32_16x16x32_bf16 v[6:9], v[142:145], v[190:193], v[6:9]
	v_mfma_f32_16x16x32_bf16 v[2:5], v[150:153], v[190:193], v[2:5]
	s_setprio 0
	s_waitcnt vmcnt(8)
	s_barrier
	s_add_i32 s84, s84, 2
	s_add_u32 s46, s46, 0x100
	s_addc_u32 s47, s47, 0
	s_add_u32 s80, s80, 0x100
	s_addc_u32 s81, s81, 0
	s_cmp_gt_u32 s84, 29
	s_cbranch_scc0 .LBB0_904
	s_and_b64 vcc, exec, s[16:17]
	s_mov_b32 s50, 0x90000
	s_mov_b32 s51, 0xa0000
	s_mov_b32 s82, 0xb0000
	s_cbranch_vccz .LBB0_907
	s_barrier
